# row passes: streaming x / y loads marked nt (on top of write-through stores + MLA static prio)
# speedup vs baseline: 1.0071x; 1.0071x over previous
; __device__ __forceinline__ float bf2f(unsigned h) { return __uint_as_float(h << 16); }
; template <int MODE> ...
;     for (int m = RPW * gw; m < M_TOK; m += RPW * NGW) {
;         f32x4 xv[RPW][8]; v2u yy[RPW][8];
; #pragma unroll
;         for (int rr = 0; rr < RPW; ++rr) {
;             const float* xr = ((MODE == 0 || xin != nullptr) ? xin : xres) + (size_t)(m + rr) * DM + lane * 4;
; #pragma unroll
;             for (int k = 0; k < 8; ++k) xv[rr][k] = *(const f32x4*)(xr + k * 256);
;             if (MODE >= 1) { const bf16_t* yr = y + (size_t)(m + rr) * 256 + lane * 4;
; #pragma unroll
;                 for (int k = 0; k < 8; ++k) yy[rr][k] = *(const v2u*)(yr + (size_t)k * ((size_t)M_TOK * 256)); }
;         }
;         if (MODE >= 1) {
;             float rstd[RPW];
; #pragma unroll
;             for (int rr = 0; rr < RPW; ++rr) { float s = 0.f;
; #pragma unroll
;                 for (int k = 0; k < 8; ++k)
; #pragma unroll
;                     for (int e = 0; e < 2; ++e) { const float a = bf2f(yy[rr][k][e] & 0xffffu), b = bf2f(yy[rr][k][e] >> 16); s += a * a + b * b; }
;                 rstd[rr] = 1.0f / sqrtf(wave_sum(s) * (1.f / DM) + RMS_EPS); }
; #pragma unroll
;             for (int k = 0; k < 8; ++k) { const f32x4 g = *(const f32x4*)(gpost + k * 256 + lane * 4);
; #pragma unroll
;                 for (int rr = 0; rr < RPW; ++rr) { f32x4 yv;
;                     yv[0] = bf2f(yy[rr][k][0] & 0xffffu); yv[1] = bf2f(yy[rr][k][0] >> 16); yv[2] = bf2f(yy[rr][k][1] & 0xffffu); yv[3] = bf2f(yy[rr][k][1] >> 16);
;                     xv[rr][k] += yv * rstd[rr] * g; } }
;         }
;         if (MODE != 0)
; #pragma unroll
;         for (int rr = 0; rr < RPW; ++rr) { float* xo = xres + (size_t)(m + rr) * DM + lane * 4;
; #pragma unroll
;             for (int k = 0; k < 8; ++k) *(f32x4*)(xo + k * 256) = xv[rr][k]; }
;         if (MODE <= 1) {
;             float rstd[RPW];
; #pragma unroll
;             for (int rr = 0; rr < RPW; ++rr) { float s = 0.f;
; #pragma unroll
;                 for (int k = 0; k < 8; ++k) s += (xv[rr][k][0] * xv[rr][k][0] + xv[rr][k][1] * xv[rr][k][1]) + (xv[rr][k][2] * xv[rr][k][2] + xv[rr][k][3] * xv[rr][k][3]);
.LBB0_137:
	global_load_dwordx4 v[46:49], v[68:69], off offset:-4096 nt
	global_load_dwordx4 v[42:45], v[68:69], off offset:-3072 nt
	global_load_dwordx4 v[38:41], v[68:69], off offset:-2048 nt
	global_load_dwordx4 v[34:37], v[68:69], off offset:-1024 nt
	v_add_co_u32_e32 v70, vcc, 0xffffe000, v68
	global_load_dwordx4 v[54:57], v[68:69], off nt
	global_load_dwordx4 v[50:53], v[68:69], off offset:1024 nt
	global_load_dwordx4 v[62:65], v[68:69], off offset:2048 nt
	global_load_dwordx4 v[58:61], v[68:69], off offset:3072 nt
	v_addc_co_u32_e32 v71, vcc, -1, v69, vcc
	global_load_dwordx4 v[88:91], v[70:71], off nt
	v_add_co_u32_e32 v104, vcc, 0xfffff000, v68
	v_add_co_u32_e64 v72, s[4:5], s16, v66
	s_nop 0
	v_addc_co_u32_e32 v105, vcc, -1, v69, vcc
	v_add_co_u32_e32 v70, vcc, s0, v68
	global_load_dwordx4 v[92:95], v[104:105], off offset:-3072 nt
	global_load_dwordx4 v[96:99], v[104:105], off offset:-2048 nt
	global_load_dwordx4 v[100:103], v[104:105], off offset:-1024 nt
	v_addc_co_u32_e32 v71, vcc, 0, v69, vcc
	global_load_dwordx4 v[104:107], v[70:71], off nt
	global_load_dwordx4 v[108:111], v[70:71], off offset:1024 nt
	global_load_dwordx4 v[112:115], v[70:71], off offset:2048 nt
	global_load_dwordx4 v[116:119], v[70:71], off offset:3072 nt
	v_addc_co_u32_e64 v73, s[4:5], -1, v67, s[4:5]
	v_add_co_u32_e64 v74, s[4:5], s17, v66
	s_add_i32 s8, s8, s10
	s_nop 0
	v_addc_co_u32_e64 v75, s[4:5], -1, v67, s[4:5]
	v_add_co_u32_e64 v76, s[4:5], s18, v66
	s_cmpk_gt_i32 s8, 0x3fff
	s_nop 0
	v_addc_co_u32_e64 v77, s[4:5], -1, v67, s[4:5]
	v_add_co_u32_e64 v78, s[4:5], s19, v66
	v_lshl_add_u64 v[68:69], v[68:69], 0, s[14:15]
	s_nop 0
	v_addc_co_u32_e64 v79, s[4:5], -1, v67, s[4:5]
	v_add_co_u32_e64 v80, s[4:5], s20, v66
	s_waitcnt vmcnt(15)
	v_mul_f32_e32 v70, v47, v47
	v_mul_f32_e32 v71, v49, v49
	s_waitcnt vmcnt(14)
	v_mul_f32_e32 v87, v43, v43
	v_mul_f32_e32 v120, v45, v45
	s_waitcnt vmcnt(13)
	v_mul_f32_e32 v121, v39, v39
	v_mul_f32_e32 v122, v41, v41
	s_waitcnt vmcnt(12)
	v_mul_f32_e32 v123, v35, v35
	v_mul_f32_e32 v124, v37, v37
	s_waitcnt vmcnt(11)
	v_mul_f32_e32 v125, v55, v55
	v_mul_f32_e32 v126, v57, v57
	s_waitcnt vmcnt(10)
	v_mul_f32_e32 v127, v51, v51
	v_mul_f32_e32 v128, v53, v53
	s_waitcnt vmcnt(9)
	v_mul_f32_e32 v129, v63, v63
	v_mul_f32_e32 v130, v65, v65
	v_fmac_f32_e32 v70, v46, v46
	v_fmac_f32_e32 v71, v48, v48
	v_fmac_f32_e32 v87, v42, v42
	v_fmac_f32_e32 v120, v44, v44
	v_fmac_f32_e32 v121, v38, v38
	v_fmac_f32_e32 v122, v40, v40
	v_fmac_f32_e32 v123, v34, v34
	v_fmac_f32_e32 v124, v36, v36
	v_fmac_f32_e32 v125, v54, v54
	v_fmac_f32_e32 v126, v56, v56
	v_fmac_f32_e32 v127, v50, v50
	v_fmac_f32_e32 v128, v52, v52
	v_fmac_f32_e32 v129, v62, v62
	v_fmac_f32_e32 v130, v64, v64
	v_add_f32_e32 v70, v70, v71
	s_waitcnt vmcnt(7)
	v_mul_f32_e32 v71, v89, v89
	v_add_f32_e32 v87, v87, v120
	v_mul_f32_e32 v120, v91, v91
	v_add_f32_e32 v121, v121, v122
	v_add_f32_e32 v122, v123, v124
	v_add_f32_e32 v123, v125, v126
	v_add_f32_e32 v124, v127, v128
	v_mul_f32_e32 v131, v59, v59
	v_mul_f32_e32 v132, v61, v61
	v_add_f32_e32 v125, v129, v130
	v_fmac_f32_e32 v71, v88, v88
	v_fmac_f32_e32 v120, v90, v90
	s_waitcnt vmcnt(6)
	v_mul_f32_e32 v127, v93, v93
	v_mul_f32_e32 v128, v95, v95
	v_add_f32_e32 v123, v123, v124
	v_fmac_f32_e32 v131, v58, v58
	v_fmac_f32_e32 v132, v60, v60
	s_waitcnt vmcnt(5)
	v_mul_f32_e32 v129, v97, v97
	v_mul_f32_e32 v130, v99, v99
	v_add_f32_e32 v71, v71, v120
	v_fmac_f32_e32 v127, v92, v92
	v_fmac_f32_e32 v128, v94, v94
	v_add_f32_e32 v120, v123, v125
	s_waitcnt vmcnt(3)
	v_mul_f32_e32 v123, v105, v105
	v_mul_f32_e32 v124, v107, v107
	v_add_f32_e32 v126, v131, v132
	v_mul_f32_e32 v131, v101, v101
	v_mul_f32_e32 v132, v103, v103
	v_fmac_f32_e32 v129, v96, v96
	v_fmac_f32_e32 v130, v98, v98
	s_waitcnt vmcnt(2)
	v_mul_f32_e32 v125, v109, v109
	v_mul_f32_e32 v133, v111, v111
	v_add_f32_e32 v127, v127, v128
	v_fmac_f32_e32 v123, v104, v104
	v_fmac_f32_e32 v124, v106, v106
	v_fmac_f32_e32 v131, v100, v100
	v_fmac_f32_e32 v132, v102, v102
	s_waitcnt vmcnt(1)
	v_mul_f32_e32 v134, v113, v113
	v_mul_f32_e32 v135, v115, v115
	v_add_f32_e32 v128, v129, v130
	v_add_f32_e32 v120, v120, v126
	v_fmac_f32_e32 v125, v108, v108
	v_fmac_f32_e32 v133, v110, v110
	v_add_f32_e32 v71, v71, v127
	v_add_f32_e32 v123, v123, v124
	s_waitcnt vmcnt(0)
; template <int MODE> ...
;     ...
;             for (int rr = 0; rr < RPW; ++rr) { float s = 0.f;
; #pragma unroll
;                 for (int k = 0; k < 8; ++k) s += (xv[rr][k][0] * xv[rr][k][0] + xv[rr][k][1] * xv[rr][k][1]) + (xv[rr][k][2] * xv[rr][k][2] + xv[rr][k][3] * xv[rr][k][3]);
;                 rstd[rr] = 1.0f / sqrtf(wave_sum(s) * (1.f / DM) + RMS_EPS); }
; #pragma unroll
;             for (int k = 0; k < 8; ++k) { const f32x4 g = *(const f32x4*)(gpre + k * 256 + lane * 4);
; #pragma unroll
;                 for (int rr = 0; rr < RPW; ++rr) { const f32x4 a = xv[rr][k] * rstd[rr] * g;
	v_mul_f32_e32 v136, v117, v117
	v_mul_f32_e32 v137, v119, v119
	v_add_f32_e32 v129, v131, v132
	v_fmac_f32_e32 v134, v112, v112
	v_fmac_f32_e32 v135, v114, v114
	v_add_f32_e32 v124, v125, v133
	v_add_f32_e32 v71, v71, v128
	v_add_f32_e32 v120, v120, v123
	v_fmac_f32_e32 v136, v116, v116
	v_fmac_f32_e32 v137, v118, v118
	v_add_f32_e32 v125, v134, v135
	v_add_f32_e32 v71, v71, v129
	v_add_f32_e32 v120, v120, v124
	v_add_f32_e32 v126, v136, v137
	v_add_f32_e32 v70, v71, v70
	v_add_f32_e32 v71, v120, v125
	v_add_f32_e32 v70, v70, v87
	v_add_f32_e32 v71, v71, v126
	v_add_f32_e32 v70, v70, v121
	v_add_f32_e32 v70, v70, v122
	v_add_f32_dpp v71, v71, v71 quad_perm:[1,0,3,2] row_mask:0xf bank_mask:0xf bound_ctrl:1
	v_addc_co_u32_e64 v81, s[4:5], -1, v67, s[4:5]
	s_nop 0
	v_add_f32_dpp v71, v71, v71 quad_perm:[2,3,0,1] row_mask:0xf bank_mask:0xf bound_ctrl:1
	v_add_f32_dpp v70, v70, v70 quad_perm:[1,0,3,2] row_mask:0xf bank_mask:0xf bound_ctrl:1
	v_add_co_u32_e64 v82, s[4:5], s21, v66
	v_add_f32_dpp v71, v71, v71 row_half_mirror row_mask:0xf bank_mask:0xf bound_ctrl:1
	v_add_f32_dpp v70, v70, v70 quad_perm:[2,3,0,1] row_mask:0xf bank_mask:0xf bound_ctrl:1
	v_addc_co_u32_e64 v83, s[4:5], -1, v67, s[4:5]
	v_add_f32_dpp v71, v71, v71 row_mirror row_mask:0xf bank_mask:0xf bound_ctrl:1
	v_add_f32_dpp v70, v70, v70 row_half_mirror row_mask:0xf bank_mask:0xf bound_ctrl:1
	v_mov_b32_e32 v87, v71
	s_nop 1
	v_permlane16_swap_b32_e32 v71, v87
	v_add_f32_dpp v70, v70, v70 row_mirror row_mask:0xf bank_mask:0xf bound_ctrl:1
	v_mov_b32_e32 v120, v70
	v_add_f32_e32 v71, v71, v87
	s_nop 0
	v_permlane16_swap_b32_e32 v70, v120
	v_mov_b32_e32 v87, v71
	v_add_f32_e32 v70, v70, v120
	s_nop 0
	v_permlane32_swap_b32_e32 v71, v87
	v_mov_b32_e32 v120, v70
	v_add_f32_e32 v71, v71, v87
	s_nop 0
	v_permlane32_swap_b32_e32 v70, v120
	v_fmamk_f32 v71, v71, 0x3a000000, v1
	v_add_co_u32_e64 v84, s[4:5], s22, v66
	v_add_f32_e32 v70, v70, v120
	v_mul_f32_e32 v87, 0x4f800000, v71
	v_cmp_gt_f32_e32 vcc, s1, v71
	v_addc_co_u32_e64 v85, s[4:5], -1, v67, s[4:5]
	v_fmamk_f32 v70, v70, 0x3a000000, v1
	v_cndmask_b32_e32 v71, v71, v87, vcc
	v_mul_f32_e32 v87, 0x4f800000, v70
	v_sqrt_f32_e32 v120, v71
	v_cmp_gt_f32_e64 s[4:5], s1, v70
	v_add_u32_e32 v121, -1, v120
	s_nop 0
	v_cndmask_b32_e64 v70, v70, v87, s[4:5]
	v_sqrt_f32_e32 v87, v70
	v_add_u32_e32 v122, 1, v120
	v_fma_f32 v123, -v121, v120, v71
	v_fma_f32 v124, -v122, v120, v71
	v_add_u32_e32 v125, -1, v87
	v_cmp_ge_f32_e64 s[6:7], 0, v123
	v_add_u32_e32 v126, 1, v87
	v_fma_f32 v123, -v126, v87, v70
	v_cndmask_b32_e64 v120, v120, v121, s[6:7]
	v_cmp_lt_f32_e64 s[6:7], 0, v124
	v_fma_f32 v121, -v125, v87, v70
	s_nop 0
	v_cndmask_b32_e64 v120, v120, v122, s[6:7]
	v_cmp_ge_f32_e64 s[6:7], 0, v121
	v_mul_f32_e32 v121, 0x37800000, v120
	v_cndmask_b32_e32 v120, v120, v121, vcc
	v_cndmask_b32_e64 v87, v87, v125, s[6:7]
	v_cmp_lt_f32_e64 s[6:7], 0, v123
	v_cmp_class_f32_e32 vcc, v71, v86
	s_nop 0
	v_cndmask_b32_e64 v87, v87, v126, s[6:7]
	v_mul_f32_e32 v121, 0x37800000, v87
	v_cndmask_b32_e32 v71, v120, v71, vcc
	v_cndmask_b32_e64 v87, v87, v121, s[4:5]
	v_cmp_class_f32_e32 vcc, v70, v86
	v_div_scale_f32 v120, s[4:5], v71, v71, 1.0
	s_nop 0
	v_cndmask_b32_e32 v70, v87, v70, vcc
	v_rcp_f32_e32 v87, v120
	v_div_scale_f32 v122, s[6:7], v70, v70, 1.0
	v_rcp_f32_e32 v124, v122
	v_fma_f32 v125, -v120, v87, 1.0
	v_div_scale_f32 v121, s[4:5], 1.0, v71, 1.0
	v_fmac_f32_e32 v87, v125, v87
	v_fma_f32 v125, -v122, v124, 1.0
	v_div_scale_f32 v123, vcc, 1.0, v70, 1.0
	v_mul_f32_e32 v126, v121, v87
	v_fmac_f32_e32 v124, v125, v124
	v_fma_f32 v125, -v120, v126, v121
	v_mul_f32_e32 v127, v123, v124
	v_fmac_f32_e32 v126, v125, v87
	v_fma_f32 v125, -v122, v127, v123
	v_fmac_f32_e32 v127, v125, v124
	v_fma_f32 v120, -v120, v126, v121
	v_fma_f32 v121, -v122, v127, v123
	v_div_fmas_f32 v121, v121, v124, v127
	s_mov_b64 vcc, s[4:5]
	v_div_fixup_f32 v70, v121, v70, 1.0
	v_div_fmas_f32 v87, v120, v87, v126
	v_pk_mul_f32 v[88:89], v[88:89], v[70:71] op_sel_hi:[1,0]
	v_pk_mul_f32 v[90:91], v[90:91], v[70:71] op_sel_hi:[1,0]
	v_pk_mul_f32 v[92:93], v[92:93], v[70:71] op_sel_hi:[1,0]
	v_pk_mul_f32 v[94:95], v[94:95], v[70:71] op_sel_hi:[1,0]
	v_pk_mul_f32 v[96:97], v[96:97], v[70:71] op_sel_hi:[1,0]
	v_pk_mul_f32 v[98:99], v[98:99], v[70:71] op_sel_hi:[1,0]
	v_pk_mul_f32 v[100:101], v[100:101], v[70:71] op_sel_hi:[1,0]
	v_pk_mul_f32 v[102:103], v[102:103], v[70:71] op_sel_hi:[1,0]
	v_pk_mul_f32 v[46:47], v[46:47], v[70:71] op_sel_hi:[1,0]
	v_pk_mul_f32 v[48:49], v[48:49], v[70:71] op_sel_hi:[1,0]
	v_pk_mul_f32 v[42:43], v[42:43], v[70:71] op_sel_hi:[1,0]
	v_pk_mul_f32 v[44:45], v[44:45], v[70:71] op_sel_hi:[1,0]
	v_pk_mul_f32 v[38:39], v[38:39], v[70:71] op_sel_hi:[1,0]
	v_pk_mul_f32 v[40:41], v[40:41], v[70:71] op_sel_hi:[1,0]
	v_pk_mul_f32 v[34:35], v[34:35], v[70:71] op_sel_hi:[1,0]
	v_pk_mul_f32 v[36:37], v[36:37], v[70:71] op_sel_hi:[1,0]
	v_div_fixup_f32 v70, v87, v71, 1.0
	v_pk_mul_f32 v[54:55], v[54:55], v[70:71] op_sel_hi:[1,0]
	v_pk_mul_f32 v[56:57], v[56:57], v[70:71] op_sel_hi:[1,0]
	v_pk_mul_f32 v[88:89], v[2:3], v[88:89]
	v_pk_mul_f32 v[90:91], v[4:5], v[90:91]
	v_pk_mul_f32 v[92:93], v[6:7], v[92:93]
	v_pk_mul_f32 v[38:39], v[26:27], v[38:39]
	v_pk_mul_f32 v[40:41], v[28:29], v[40:41]
	v_pk_mul_f32 v[34:35], v[30:31], v[34:35]
	v_pk_mul_f32 v[36:37], v[32:33], v[36:37]
	v_pk_mul_f32 v[50:51], v[50:51], v[70:71] op_sel_hi:[1,0]
	v_pk_mul_f32 v[52:53], v[52:53], v[70:71] op_sel_hi:[1,0]
	v_pk_mul_f32 v[62:63], v[62:63], v[70:71] op_sel_hi:[1,0]
	v_pk_mul_f32 v[64:65], v[64:65], v[70:71] op_sel_hi:[1,0]
	v_pk_mul_f32 v[58:59], v[58:59], v[70:71] op_sel_hi:[1,0]
; __device__ __forceinline__ unsigned pk2(float lo, float hi) { return f2bf(lo) | (f2bf(hi) << 16); }
; template <int MODE> ...
;     ...
; #pragma unroll
;             for (int k = 0; k < 8; ++k) { const f32x4 g = *(const f32x4*)(gpre + k * 256 + lane * 4);
; #pragma unroll
;                 for (int rr = 0; rr < RPW; ++rr) { const f32x4 a = xv[rr][k] * rstd[rr] * g;
;                     v2u o; o.x = pk2(a[0], a[1]); o.y = pk2(a[2], a[3]);
;                     *(v2u*)(h + ((size_t)(k * 4 + (lane >> 4)) * M_TOK + (m + rr)) * 64 + (lane & 15) * 4) = o; } }
	v_pk_mul_f32 v[60:61], v[60:61], v[70:71] op_sel_hi:[1,0]
	v_pk_mul_f32 v[104:105], v[104:105], v[70:71] op_sel_hi:[1,0]
	v_pk_mul_f32 v[106:107], v[106:107], v[70:71] op_sel_hi:[1,0]
	v_pk_mul_f32 v[108:109], v[108:109], v[70:71] op_sel_hi:[1,0]
	v_pk_mul_f32 v[110:111], v[110:111], v[70:71] op_sel_hi:[1,0]
	v_pk_mul_f32 v[112:113], v[112:113], v[70:71] op_sel_hi:[1,0]
	v_pk_mul_f32 v[114:115], v[114:115], v[70:71] op_sel_hi:[1,0]
	v_pk_mul_f32 v[116:117], v[116:117], v[70:71] op_sel_hi:[1,0]
	v_pk_mul_f32 v[70:71], v[118:119], v[70:71] op_sel_hi:[1,0]
	v_pk_mul_f32 v[94:95], v[8:9], v[94:95]
	v_pk_mul_f32 v[96:97], v[10:11], v[96:97]
	v_pk_mul_f32 v[98:99], v[12:13], v[98:99]
	v_pk_mul_f32 v[100:101], v[14:15], v[100:101]
	v_pk_mul_f32 v[102:103], v[16:17], v[102:103]
	v_pk_mul_f32 v[46:47], v[18:19], v[46:47]
	v_pk_mul_f32 v[48:49], v[20:21], v[48:49]
	v_pk_mul_f32 v[42:43], v[22:23], v[42:43]
	v_pk_mul_f32 v[44:45], v[24:25], v[44:45]
	v_bfe_u32 v87, v88, 16, 1
	v_bfe_u32 v118, v89, 16, 1
	v_bfe_u32 v119, v90, 16, 1
	v_bfe_u32 v120, v91, 16, 1
	v_bfe_u32 v121, v92, 16, 1
	v_bfe_u32 v142, v39, 16, 1
	v_bfe_u32 v143, v40, 16, 1
	v_bfe_u32 v146, v35, 16, 1
	v_bfe_u32 v147, v36, 16, 1
	v_bfe_u32 v148, v37, 16, 1
	v_pk_mul_f32 v[54:55], v[2:3], v[54:55]
	v_pk_mul_f32 v[56:57], v[4:5], v[56:57]
	v_bfe_u32 v122, v93, 16, 1
	v_bfe_u32 v123, v94, 16, 1
	v_bfe_u32 v124, v95, 16, 1
	v_bfe_u32 v125, v96, 16, 1
	v_bfe_u32 v126, v97, 16, 1
	v_bfe_u32 v127, v98, 16, 1
	v_bfe_u32 v128, v99, 16, 1
	v_bfe_u32 v129, v100, 16, 1
	v_bfe_u32 v130, v101, 16, 1
	v_bfe_u32 v131, v102, 16, 1
	v_bfe_u32 v132, v103, 16, 1
	v_bfe_u32 v133, v46, 16, 1
	v_bfe_u32 v135, v48, 16, 1
	v_bfe_u32 v137, v42, 16, 1
	v_bfe_u32 v138, v43, 16, 1
	v_bfe_u32 v139, v44, 16, 1
	v_bfe_u32 v141, v38, 16, 1
	v_bfe_u32 v144, v41, 16, 1
	v_bfe_u32 v145, v34, 16, 1
	v_pk_mul_f32 v[50:51], v[6:7], v[50:51]
	v_pk_mul_f32 v[52:53], v[8:9], v[52:53]
	v_pk_mul_f32 v[62:63], v[10:11], v[62:63]
	v_pk_mul_f32 v[64:65], v[12:13], v[64:65]
	v_pk_mul_f32 v[58:59], v[14:15], v[58:59]
	v_pk_mul_f32 v[60:61], v[16:17], v[60:61]
	v_pk_mul_f32 v[104:105], v[18:19], v[104:105]
	v_pk_mul_f32 v[106:107], v[20:21], v[106:107]
	v_pk_mul_f32 v[108:109], v[22:23], v[108:109]
	v_pk_mul_f32 v[110:111], v[24:25], v[110:111]
	v_pk_mul_f32 v[112:113], v[26:27], v[112:113]
	v_pk_mul_f32 v[114:115], v[28:29], v[114:115]
	v_pk_mul_f32 v[116:117], v[30:31], v[116:117]
	v_pk_mul_f32 v[70:71], v[32:33], v[70:71]
	v_add3_u32 v87, v88, v87, s9
	v_add3_u32 v88, v89, v118, s9
	v_add3_u32 v89, v90, v119, s9
	v_add3_u32 v90, v91, v120, s9
	v_add3_u32 v91, v92, v121, s9
	v_add3_u32 v118, v39, v142, s9
	v_add3_u32 v39, v40, v143, s9
	v_add3_u32 v120, v35, v146, s9
	v_add3_u32 v35, v36, v147, s9
	v_add3_u32 v121, v37, v148, s9
	v_bfe_u32 v36, v54, 16, 1
	v_bfe_u32 v37, v55, 16, 1
	v_bfe_u32 v40, v56, 16, 1
	v_bfe_u32 v134, v47, 16, 1
	v_bfe_u32 v136, v49, 16, 1
	v_bfe_u32 v140, v45, 16, 1
	v_add3_u32 v92, v93, v122, s9
	v_add3_u32 v93, v94, v123, s9
	v_add3_u32 v94, v95, v124, s9
	v_add3_u32 v95, v96, v125, s9
	v_add3_u32 v96, v97, v126, s9
	v_add3_u32 v97, v98, v127, s9
	v_add3_u32 v98, v99, v128, s9
	v_add3_u32 v99, v100, v129, s9
	v_add3_u32 v100, v101, v130, s9
	v_add3_u32 v101, v102, v131, s9
	v_add3_u32 v102, v103, v132, s9
	v_add3_u32 v46, v46, v133, s9
	v_add3_u32 v48, v48, v135, s9
	v_add3_u32 v42, v42, v137, s9
	v_add3_u32 v103, v43, v138, s9
	v_add3_u32 v43, v44, v139, s9
	v_add3_u32 v38, v38, v141, s9
	v_add3_u32 v119, v41, v144, s9
	v_add3_u32 v34, v34, v145, s9
	v_bfe_u32 v41, v57, 16, 1
	v_bfe_u32 v44, v50, 16, 1
	v_bfe_u32 v122, v51, 16, 1
	v_bfe_u32 v123, v52, 16, 1
	v_bfe_u32 v125, v62, 16, 1
	v_bfe_u32 v127, v64, 16, 1
	v_bfe_u32 v129, v58, 16, 1
	v_bfe_u32 v131, v60, 16, 1
	v_bfe_u32 v133, v104, 16, 1
	v_bfe_u32 v135, v106, 16, 1
	v_bfe_u32 v137, v108, 16, 1
	v_bfe_u32 v139, v110, 16, 1
	v_bfe_u32 v141, v112, 16, 1
	v_bfe_u32 v143, v114, 16, 1
	v_bfe_u32 v145, v116, 16, 1
	v_bfe_u32 v147, v70, 16, 1
	v_add3_u32 v54, v54, v36, s9
	v_add3_u32 v55, v55, v37, s9
	v_add3_u32 v56, v56, v40, s9
	v_lshrrev_b32_e32 v36, 16, v87
	v_lshrrev_b32_e32 v37, 16, v89
	v_add3_u32 v47, v47, v134, s9
	v_add3_u32 v49, v49, v136, s9
	v_add3_u32 v45, v45, v140, s9
; __device__ __forceinline__ unsigned f2bf(float f) { unsigned u = __float_as_uint(f); return (u + 0x7fffu + ((u >> 16) & 1u)) >> 16; }
; __device__ __forceinline__ unsigned pk2(float lo, float hi) { return f2bf(lo) | (f2bf(hi) << 16); }
; template <int MODE> ...
;     ...
; #pragma unroll
;             for (int k = 0; k < 8; ++k) { const f32x4 g = *(const f32x4*)(gpre + k * 256 + lane * 4);
; #pragma unroll
;                 for (int rr = 0; rr < RPW; ++rr) { const f32x4 a = xv[rr][k] * rstd[rr] * g;
;                     v2u o; o.x = pk2(a[0], a[1]); o.y = pk2(a[2], a[3]);
;                     *(v2u*)(h + ((size_t)(k * 4 + (lane >> 4)) * M_TOK + (m + rr)) * 64 + (lane & 15) * 4) = o; } }
	v_bfe_u32 v124, v53, 16, 1
	v_bfe_u32 v126, v63, 16, 1
	v_bfe_u32 v128, v65, 16, 1
	v_bfe_u32 v130, v59, 16, 1
	v_bfe_u32 v132, v61, 16, 1
	v_bfe_u32 v134, v105, 16, 1
	v_bfe_u32 v136, v107, 16, 1
	v_bfe_u32 v138, v109, 16, 1
	v_bfe_u32 v140, v111, 16, 1
	v_bfe_u32 v142, v113, 16, 1
	v_bfe_u32 v144, v115, 16, 1
	v_bfe_u32 v146, v117, 16, 1
	v_bfe_u32 v148, v71, 16, 1
	v_add3_u32 v57, v57, v41, s9
	v_add3_u32 v50, v50, v44, s9
	v_add3_u32 v51, v51, v122, s9
	v_add3_u32 v52, v52, v123, s9
	v_add3_u32 v62, v62, v125, s9
	v_add3_u32 v64, v64, v127, s9
	v_add3_u32 v58, v58, v129, s9
	v_add3_u32 v60, v60, v131, s9
	v_add3_u32 v104, v104, v133, s9
	v_add3_u32 v106, v106, v135, s9
	v_add3_u32 v108, v108, v137, s9
	v_add3_u32 v110, v110, v139, s9
	v_add3_u32 v112, v112, v141, s9
	v_add3_u32 v114, v114, v143, s9
	v_add3_u32 v116, v116, v145, s9
	v_add3_u32 v70, v70, v147, s9
	v_lshrrev_b32_e32 v40, 16, v91
	v_lshrrev_b32_e32 v41, 16, v93
	v_lshrrev_b32_e32 v44, 16, v95
	v_lshrrev_b32_e32 v87, 16, v97
	v_lshrrev_b32_e32 v89, 16, v99
	v_lshrrev_b32_e32 v91, 16, v101
	v_lshrrev_b32_e32 v46, 16, v46
	v_lshrrev_b32_e32 v48, 16, v48
	v_lshrrev_b32_e32 v93, 16, v42
	v_lshrrev_b32_e32 v95, 16, v43
	v_lshrrev_b32_e32 v97, 16, v38
	v_lshrrev_b32_e32 v99, 16, v39
	v_lshrrev_b32_e32 v101, 16, v34
	v_lshrrev_b32_e32 v122, 16, v35
	v_and_or_b32 v34, v88, s11, v36
	v_and_or_b32 v35, v90, s11, v37
	v_lshrrev_b32_e32 v54, 16, v54
	v_lshrrev_b32_e32 v56, 16, v56
	v_add3_u32 v53, v53, v124, s9
	v_add3_u32 v63, v63, v126, s9
	v_add3_u32 v65, v65, v128, s9
	v_add3_u32 v59, v59, v130, s9
	v_add3_u32 v61, v61, v132, s9
	v_add3_u32 v105, v105, v134, s9
	v_add3_u32 v107, v107, v136, s9
	v_add3_u32 v109, v109, v138, s9
	v_add3_u32 v111, v111, v140, s9
	v_add3_u32 v113, v113, v142, s9
	v_add3_u32 v115, v115, v144, s9
	v_add3_u32 v117, v117, v146, s9
	v_add3_u32 v71, v71, v148, s9
	v_and_or_b32 v36, v92, s11, v40
	v_and_or_b32 v37, v94, s11, v41
	v_and_or_b32 v38, v96, s11, v44
	v_and_or_b32 v39, v98, s11, v87
	v_and_or_b32 v40, v100, s11, v89
	v_and_or_b32 v41, v102, s11, v91
	v_and_or_b32 v42, v47, s11, v46
	v_and_or_b32 v43, v49, s11, v48
	v_and_or_b32 v44, v103, s11, v93
	v_and_or_b32 v45, v45, s11, v95
	v_and_or_b32 v46, v118, s11, v97
	v_and_or_b32 v47, v119, s11, v99
	v_and_or_b32 v48, v120, s11, v101
	v_and_or_b32 v49, v121, s11, v122
	v_lshrrev_b32_e32 v50, 16, v50
	v_lshrrev_b32_e32 v52, 16, v52
	v_lshrrev_b32_e32 v62, 16, v62
	v_lshrrev_b32_e32 v64, 16, v64
	v_lshrrev_b32_e32 v58, 16, v58
	v_lshrrev_b32_e32 v60, 16, v60
	v_lshrrev_b32_e32 v87, 16, v104
	v_lshrrev_b32_e32 v88, 16, v106
	v_lshrrev_b32_e32 v89, 16, v108
	v_lshrrev_b32_e32 v90, 16, v110
	v_lshrrev_b32_e32 v91, 16, v112
	v_lshrrev_b32_e32 v92, 16, v114
	v_lshrrev_b32_e32 v93, 16, v116
	v_lshrrev_b32_e32 v70, 16, v70
	global_store_dwordx2 v[72:73], v[34:35], off offset:-128
	v_and_or_b32 v34, v55, s11, v54
	v_and_or_b32 v35, v57, s11, v56
	global_store_dwordx2 v[74:75], v[36:37], off offset:-128
	v_and_or_b32 v36, v51, s11, v50
	v_and_or_b32 v37, v53, s11, v52
	global_store_dwordx2 v[76:77], v[38:39], off offset:-128
	v_and_or_b32 v38, v63, s11, v62
	v_and_or_b32 v39, v65, s11, v64
	global_store_dwordx2 v[78:79], v[40:41], off offset:-128
	v_and_or_b32 v40, v59, s11, v58
	v_and_or_b32 v41, v61, s11, v60
	global_store_dwordx2 v[80:81], v[42:43], off offset:-128
	v_and_or_b32 v42, v105, s11, v87
	v_and_or_b32 v43, v107, s11, v88
	global_store_dwordx2 v[82:83], v[44:45], off offset:-128
	v_and_or_b32 v44, v109, s11, v89
	v_and_or_b32 v45, v111, s11, v90
	global_store_dwordx2 v[84:85], v[46:47], off offset:-128
	v_and_or_b32 v46, v113, s11, v91
	v_and_or_b32 v47, v115, s11, v92
	global_store_dwordx2 v[66:67], v[48:49], off offset:-128
	v_and_or_b32 v48, v117, s11, v93
	v_and_or_b32 v49, v71, s11, v70
	global_store_dwordx2 v[72:73], v[34:35], off
	global_store_dwordx2 v[74:75], v[36:37], off
	global_store_dwordx2 v[76:77], v[38:39], off
	global_store_dwordx2 v[78:79], v[40:41], off
	global_store_dwordx2 v[80:81], v[42:43], off
	global_store_dwordx2 v[82:83], v[44:45], off
	global_store_dwordx2 v[84:85], v[46:47], off
	global_store_dwordx2 v[66:67], v[48:49], off
	v_lshl_add_u64 v[66:67], v[66:67], 0, s[12:13]
	s_cbranch_scc0 .LBB0_137

; __device__ __forceinline__ float bf2f(unsigned h) { return __uint_as_float(h << 16); }
; template <int MODE> ...
;     ...
; #pragma unroll
;         for (int rr = 0; rr < RPW; ++rr) {
;             const float* xr = ((MODE == 0 || xin != nullptr) ? xin : xres) + (size_t)(m + rr) * DM + lane * 4;
; #pragma unroll
;             for (int k = 0; k < 8; ++k) xv[rr][k] = *(const f32x4*)(xr + k * 256);
;             if (MODE >= 1) { const bf16_t* yr = y + (size_t)(m + rr) * 256 + lane * 4;
; #pragma unroll
;                 for (int k = 0; k < 8; ++k) yy[rr][k] = *(const v2u*)(yr + (size_t)k * ((size_t)M_TOK * 256)); }
;         }
;         if (MODE >= 1) {
;             float rstd[RPW];
; #pragma unroll
;             for (int rr = 0; rr < RPW; ++rr) { float s = 0.f;
; #pragma unroll
;                 for (int k = 0; k < 8; ++k)
; #pragma unroll
;                     for (int e = 0; e < 2; ++e) { const float a = bf2f(yy[rr][k][e] & 0xffffu), b = bf2f(yy[rr][k][e] >> 16); s += a * a + b * b; }
;                 rstd[rr] = 1.0f / sqrtf(wave_sum(s) * (1.f / DM) + RMS_EPS); }
.LBB0_225:
	v_lshl_add_u64 v[98:99], s[64:65], 0, v[146:147]
	v_add_co_u32_e32 v66, vcc, 0x1000, v98
	v_lshl_add_u64 v[100:101], v[150:151], 0, s[46:47]
	s_nop 0
	v_addc_co_u32_e32 v67, vcc, 0, v99, vcc
	v_add_co_u32_e32 v114, vcc, 0x8800000, v100
	global_load_dwordx4 v[94:97], v[98:99], off nt
	global_load_dwordx4 v[90:93], v[98:99], off offset:1024 nt
	global_load_dwordx4 v[86:89], v[98:99], off offset:2048 nt
	global_load_dwordx4 v[82:85], v[98:99], off offset:3072 nt
	v_addc_co_u32_e32 v115, vcc, 0, v101, vcc
	global_load_dwordx4 v[78:81], v[66:67], off nt
	global_load_dwordx4 v[74:77], v[66:67], off offset:1024 nt
	global_load_dwordx4 v[70:73], v[66:67], off offset:2048 nt
	s_nop 0
	global_load_dwordx4 v[66:69], v[66:67], off offset:3072 nt
	v_add_co_u32_e32 v118, vcc, 0x9000000, v100
	global_load_dwordx2 v[116:117], v[114:115], off nt
	s_nop 0
	v_addc_co_u32_e32 v119, vcc, 0, v101, vcc
	global_load_dwordx2 v[120:121], v[118:119], off nt
	v_add_co_u32_e32 v122, vcc, 0x9800000, v100
	s_add_i32 s42, s42, s18
	s_nop 0
	v_addc_co_u32_e32 v123, vcc, 0, v101, vcc
	global_load_dwordx2 v[124:125], v[122:123], off nt
	v_add_co_u32_e32 v126, vcc, 0xa000000, v100
	v_lshl_add_u64 v[150:151], v[150:151], 0, s[22:23]
	s_nop 0
	v_addc_co_u32_e32 v127, vcc, 0, v101, vcc
	global_load_dwordx2 v[128:129], v[126:127], off nt
	v_add_co_u32_e32 v152, vcc, 0xa800000, v100
	s_waitcnt vmcnt(3)
	v_lshlrev_b32_e32 v168, 16, v116
	v_addc_co_u32_e32 v153, vcc, 0, v101, vcc
	global_load_dwordx2 v[154:155], v[152:153], off nt
	v_add_co_u32_e32 v156, vcc, 0xb000000, v100
	v_and_b32_e32 v169, 0xffff0000, v116
	s_nop 0
	v_addc_co_u32_e32 v157, vcc, 0, v101, vcc
	global_load_dwordx2 v[158:159], v[156:157], off nt
	v_add_co_u32_e32 v160, vcc, 0xb800000, v100
	v_lshlrev_b32_e32 v116, 16, v117
	s_nop 0
	v_addc_co_u32_e32 v161, vcc, 0, v101, vcc
	global_load_dwordx2 v[162:163], v[160:161], off nt
	v_add_co_u32_e32 v164, vcc, 0xc000000, v100
	v_and_b32_e32 v117, 0xffff0000, v117
	s_nop 0
	v_addc_co_u32_e32 v165, vcc, 0, v101, vcc
	global_load_dwordx2 v[166:167], v[164:165], off nt
	v_add_co_u32_e32 v100, vcc, s31, v98
	v_mul_f32_e32 v1, v169, v169
	s_nop 0
	v_addc_co_u32_e32 v101, vcc, 0, v99, vcc
	v_add_co_u32_e32 v130, vcc, s33, v98
	v_mul_f32_e32 v170, v117, v117
	s_nop 0
	v_addc_co_u32_e32 v131, vcc, 0, v99, vcc
	global_load_dwordx4 v[110:113], v[130:131], off offset:-4096 nt
	global_load_dwordx4 v[106:109], v[100:101], off offset:1024 nt
	global_load_dwordx4 v[102:105], v[100:101], off offset:2048 nt
	s_nop 0
	global_load_dwordx4 v[98:101], v[100:101], off offset:3072 nt
	s_nop 0
	global_load_dwordx4 v[142:145], v[130:131], off nt
	global_load_dwordx4 v[138:141], v[130:131], off offset:1024 nt
	global_load_dwordx4 v[134:137], v[130:131], off offset:2048 nt
	s_nop 0
	global_load_dwordx4 v[130:133], v[130:131], off offset:3072 nt
	s_nop 0
	global_load_dwordx2 v[114:115], v[114:115], off offset:512 nt
	s_nop 0
	global_load_dwordx2 v[118:119], v[118:119], off offset:512 nt
	s_nop 0
	global_load_dwordx2 v[122:123], v[122:123], off offset:512 nt
	s_nop 0
	global_load_dwordx2 v[126:127], v[126:127], off offset:512 nt
	s_nop 0
	global_load_dwordx2 v[152:153], v[152:153], off offset:512 nt
	s_nop 0
	global_load_dwordx2 v[156:157], v[156:157], off offset:512 nt
	s_nop 0
	global_load_dwordx2 v[160:161], v[160:161], off offset:512 nt
	s_nop 0
	global_load_dwordx2 v[164:165], v[164:165], off offset:512 nt
	v_fmac_f32_e32 v1, v168, v168
	v_fmac_f32_e32 v170, v116, v116
	s_waitcnt vmcnt(22)
	v_and_b32_e32 v171, 0xffff0000, v120
	v_add_f32_e32 v1, v1, v170
	v_lshlrev_b32_e32 v170, 16, v120
	v_mul_f32_e32 v120, v171, v171
	v_fmac_f32_e32 v120, v170, v170
	v_add_f32_e32 v1, v1, v120
	v_lshlrev_b32_e32 v120, 16, v121
	v_and_b32_e32 v121, 0xffff0000, v121
	v_mul_f32_e32 v172, v121, v121
	v_fmac_f32_e32 v172, v120, v120
	s_waitcnt vmcnt(21)
	v_and_b32_e32 v173, 0xffff0000, v124
	v_add_f32_e32 v1, v172, v1
	v_lshlrev_b32_e32 v172, 16, v124
	v_mul_f32_e32 v124, v173, v173
	v_fmac_f32_e32 v124, v172, v172
	v_and_b32_e32 v175, 0xffff0000, v125
	v_add_f32_e32 v1, v124, v1
	v_lshlrev_b32_e32 v174, 16, v125
	v_mul_f32_e32 v124, v175, v175
	v_fmac_f32_e32 v124, v174, v174
	s_waitcnt vmcnt(20)
	v_and_b32_e32 v177, 0xffff0000, v128
	v_add_f32_e32 v1, v124, v1
	v_lshlrev_b32_e32 v176, 16, v128
	v_mul_f32_e32 v124, v177, v177
	v_fmac_f32_e32 v124, v176, v176
	v_and_b32_e32 v179, 0xffff0000, v129
	v_add_f32_e32 v1, v124, v1
	v_lshlrev_b32_e32 v178, 16, v129
	v_mul_f32_e32 v124, v179, v179
	v_fmac_f32_e32 v124, v178, v178
	v_add_f32_e32 v1, v124, v1
	s_waitcnt vmcnt(19)
	v_and_b32_e32 v181, 0xffff0000, v154
	v_lshlrev_b32_e32 v180, 16, v154
	v_mul_f32_e32 v124, v181, v181
	v_fmac_f32_e32 v124, v180, v180
	v_lshlrev_b32_e32 v154, 16, v155
	v_and_b32_e32 v155, 0xffff0000, v155
	v_add_f32_e32 v1, v124, v1
	v_mul_f32_e32 v124, v155, v155
	v_fmac_f32_e32 v124, v154, v154
	s_waitcnt vmcnt(18)
	v_and_b32_e32 v183, 0xffff0000, v158
	v_add_f32_e32 v1, v124, v1
	v_lshlrev_b32_e32 v182, 16, v158
	v_mul_f32_e32 v124, v183, v183
	v_fmac_f32_e32 v124, v182, v182
	v_lshlrev_b32_e32 v158, 16, v159
	v_and_b32_e32 v159, 0xffff0000, v159
	v_add_f32_e32 v1, v124, v1
	v_mul_f32_e32 v124, v159, v159
	v_fmac_f32_e32 v124, v158, v158
	s_waitcnt vmcnt(17)
	v_and_b32_e32 v185, 0xffff0000, v162
	v_add_f32_e32 v1, v124, v1
	v_lshlrev_b32_e32 v184, 16, v162
	v_mul_f32_e32 v124, v185, v185
	v_fmac_f32_e32 v124, v184, v184
	v_lshlrev_b32_e32 v162, 16, v163
	v_and_b32_e32 v163, 0xffff0000, v163
	v_add_f32_e32 v1, v124, v1
	v_mul_f32_e32 v124, v163, v163
	v_fmac_f32_e32 v124, v162, v162
	s_waitcnt vmcnt(16)
; __device__ __forceinline__ float bf2f(unsigned h) { return __uint_as_float(h << 16); }
; __device__ __forceinline__ float wave_sum(float v) {
;     v += __uint_as_float(__builtin_amdgcn_mov_dpp(__float_as_uint(v), 0xB1, 0xF, 0xF, true));
;     v += __uint_as_float(__builtin_amdgcn_mov_dpp(__float_as_uint(v), 0x4E, 0xF, 0xF, true));
;     v += __uint_as_float(__builtin_amdgcn_mov_dpp(__float_as_uint(v), 0x141, 0xF, 0xF, true));
;     v += __uint_as_float(__builtin_amdgcn_mov_dpp(__float_as_uint(v), 0x140, 0xF, 0xF, true));
;     { auto rr = __builtin_amdgcn_permlane16_swap(__float_as_uint(v), __float_as_uint(v), false, false); v = __uint_as_float(rr[0]) + __uint_as_float(rr[1]); }
;     { auto rr = __builtin_amdgcn_permlane32_swap(__float_as_uint(v), __float_as_uint(v), false, false); v = __uint_as_float(rr[0]) + __uint_as_float(rr[1]); }
;     return v;
; }
; template <int MODE> ...
;     ...
;             for (int rr = 0; rr < RPW; ++rr) { float s = 0.f;
; #pragma unroll
;                 for (int k = 0; k < 8; ++k)
; #pragma unroll
;                     for (int e = 0; e < 2; ++e) { const float a = bf2f(yy[rr][k][e] & 0xffffu), b = bf2f(yy[rr][k][e] >> 16); s += a * a + b * b; }
;                 rstd[rr] = 1.0f / sqrtf(wave_sum(s) * (1.f / DM) + RMS_EPS); }
	v_and_b32_e32 v187, 0xffff0000, v166
	v_add_f32_e32 v1, v124, v1
	v_lshlrev_b32_e32 v186, 16, v166
	v_mul_f32_e32 v124, v187, v187
	v_fmac_f32_e32 v124, v186, v186
	v_lshlrev_b32_e32 v166, 16, v167
	v_and_b32_e32 v167, 0xffff0000, v167
	v_add_f32_e32 v1, v124, v1
	v_mul_f32_e32 v124, v167, v167
	v_fmac_f32_e32 v124, v166, v166
	v_add_f32_e32 v1, v124, v1
	s_waitcnt vmcnt(6)
	v_and_b32_e32 v191, 0xffff0000, v118
	v_lshlrev_b32_e32 v190, 16, v118
	v_add_f32_dpp v1, v1, v1 quad_perm:[1,0,3,2] row_mask:0xf bank_mask:0xf bound_ctrl:1
	v_mul_f32_e32 v118, v191, v191
	v_fmac_f32_e32 v118, v190, v190
	v_add_f32_dpp v1, v1, v1 quad_perm:[2,3,0,1] row_mask:0xf bank_mask:0xf bound_ctrl:1
	v_and_b32_e32 v193, 0xffff0000, v119
	v_lshlrev_b32_e32 v192, 16, v119
	v_add_f32_dpp v1, v1, v1 row_half_mirror row_mask:0xf bank_mask:0xf bound_ctrl:1
	s_waitcnt vmcnt(5)
	v_and_b32_e32 v195, 0xffff0000, v122
	v_lshlrev_b32_e32 v194, 16, v122
	v_add_f32_dpp v1, v1, v1 row_mirror row_mask:0xf bank_mask:0xf bound_ctrl:1
	v_mov_b32_e32 v124, v1
	s_nop 1
	v_permlane16_swap_b32_e32 v1, v124
	v_add_f32_e32 v1, v1, v124
	v_mov_b32_e32 v124, v1
	s_nop 1
	v_permlane32_swap_b32_e32 v1, v124
	v_add_f32_e32 v1, v1, v124
	v_fmamk_f32 v1, v1, 0x3a000000, v218
	v_cmp_gt_f32_e32 vcc, s30, v1
	v_mul_f32_e32 v124, 0x4f800000, v1
	v_and_b32_e32 v197, 0xffff0000, v123
	v_cndmask_b32_e32 v1, v1, v124, vcc
	v_sqrt_f32_e32 v124, v1
	v_lshlrev_b32_e32 v196, 16, v123
	s_waitcnt vmcnt(4)
	v_and_b32_e32 v199, 0xffff0000, v126
	v_lshlrev_b32_e32 v198, 16, v126
	v_add_u32_e32 v125, -1, v124
	v_fma_f32 v128, -v125, v124, v1
	v_cmp_ge_f32_e64 s[40:41], 0, v128
	v_add_u32_e32 v128, 1, v124
	v_and_b32_e32 v201, 0xffff0000, v127
	v_cndmask_b32_e64 v125, v124, v125, s[40:41]
	v_fma_f32 v124, -v128, v124, v1
	v_cmp_lt_f32_e64 s[40:41], 0, v124
	v_lshlrev_b32_e32 v200, 16, v127
	s_waitcnt vmcnt(3)
	v_and_b32_e32 v203, 0xffff0000, v152
	v_cndmask_b32_e64 v124, v125, v128, s[40:41]
	v_mul_f32_e32 v125, 0x37800000, v124
	v_cndmask_b32_e32 v124, v124, v125, vcc
	v_cmp_class_f32_e32 vcc, v1, v215
	v_lshlrev_b32_e32 v202, 16, v152
	v_lshlrev_b32_e32 v152, 16, v153
	v_cndmask_b32_e32 v1, v124, v1, vcc
	v_div_scale_f32 v124, s[0:1], v1, v1, 1.0
	v_rcp_f32_e32 v125, v124
	v_and_b32_e32 v153, 0xffff0000, v153
	s_waitcnt vmcnt(2)
	v_and_b32_e32 v205, 0xffff0000, v156
	v_lshlrev_b32_e32 v204, 16, v156
	v_fma_f32 v128, -v124, v125, 1.0
	v_fmac_f32_e32 v125, v128, v125
	v_div_scale_f32 v128, vcc, 1.0, v1, 1.0
	v_mul_f32_e32 v129, v128, v125
	v_fma_f32 v188, -v124, v129, v128
	v_fmac_f32_e32 v129, v188, v125
	v_fma_f32 v124, -v124, v129, v128
	v_div_fmas_f32 v124, v124, v125, v129
	v_div_fixup_f32 v188, v124, v1, 1.0
	v_lshlrev_b32_e32 v124, 16, v114
	v_and_b32_e32 v125, 0xffff0000, v114
	v_lshlrev_b32_e32 v114, 16, v115
	v_and_b32_e32 v115, 0xffff0000, v115
	v_mul_f32_e32 v1, v125, v125
	v_mul_f32_e32 v128, v115, v115
	v_fmac_f32_e32 v1, v124, v124
	v_fmac_f32_e32 v128, v114, v114
	v_add_f32_e32 v1, v1, v128
	v_add_f32_e32 v1, v1, v118
	v_mul_f32_e32 v118, v193, v193
	v_fmac_f32_e32 v118, v192, v192
	v_add_f32_e32 v1, v118, v1
	v_mul_f32_e32 v118, v195, v195
	v_fmac_f32_e32 v118, v194, v194
	v_add_f32_e32 v1, v118, v1
	v_mul_f32_e32 v118, v197, v197
	v_fmac_f32_e32 v118, v196, v196
	v_add_f32_e32 v1, v118, v1
	v_mul_f32_e32 v118, v199, v199
	v_fmac_f32_e32 v118, v198, v198
	v_add_f32_e32 v1, v118, v1
	v_mul_f32_e32 v118, v201, v201
	v_fmac_f32_e32 v118, v200, v200
	v_add_f32_e32 v1, v118, v1
	v_mul_f32_e32 v118, v203, v203
	v_fmac_f32_e32 v118, v202, v202
	v_add_f32_e32 v1, v118, v1
	v_mul_f32_e32 v118, v153, v153
	v_fmac_f32_e32 v118, v152, v152
	v_add_f32_e32 v1, v118, v1
	v_mul_f32_e32 v118, v205, v205
	v_fmac_f32_e32 v118, v204, v204
	v_lshlrev_b32_e32 v156, 16, v157
	v_and_b32_e32 v157, 0xffff0000, v157
	v_add_f32_e32 v1, v118, v1
	v_mul_f32_e32 v118, v157, v157
	v_fmac_f32_e32 v118, v156, v156
	s_waitcnt vmcnt(1)
	v_and_b32_e32 v207, 0xffff0000, v160
	v_add_f32_e32 v1, v118, v1
	v_lshlrev_b32_e32 v206, 16, v160
	v_mul_f32_e32 v118, v207, v207
	v_fmac_f32_e32 v118, v206, v206
	v_lshlrev_b32_e32 v160, 16, v161
	v_and_b32_e32 v161, 0xffff0000, v161
	v_add_f32_e32 v1, v118, v1
	v_mul_f32_e32 v118, v161, v161
	v_fmac_f32_e32 v118, v160, v160
	s_waitcnt vmcnt(0)
; __device__ __forceinline__ float bf2f(unsigned h) { return __uint_as_float(h << 16); }
; template <int MODE> ...
;     ...
;                 rstd[rr] = 1.0f / sqrtf(wave_sum(s) * (1.f / DM) + RMS_EPS); }
; #pragma unroll
;             for (int k = 0; k < 8; ++k) { const f32x4 g = *(const f32x4*)(gpost + k * 256 + lane * 4);
; #pragma unroll
;                 for (int rr = 0; rr < RPW; ++rr) { f32x4 yv;
;                     yv[0] = bf2f(yy[rr][k][0] & 0xffffu); yv[1] = bf2f(yy[rr][k][0] >> 16); yv[2] = bf2f(yy[rr][k][1] & 0xffffu); yv[3] = bf2f(yy[rr][k][1] >> 16);
;                     xv[rr][k] += yv * rstd[rr] * g; } }
	v_and_b32_e32 v209, 0xffff0000, v164
	v_add_f32_e32 v1, v118, v1
	v_lshlrev_b32_e32 v208, 16, v164
	v_mul_f32_e32 v118, v209, v209
	v_fmac_f32_e32 v118, v208, v208
	v_lshlrev_b32_e32 v164, 16, v165
	v_and_b32_e32 v165, 0xffff0000, v165
	v_add_f32_e32 v1, v118, v1
	v_mul_f32_e32 v118, v165, v165
	v_fmac_f32_e32 v118, v164, v164
	v_add_f32_e32 v1, v118, v1
	v_pk_mul_f32 v[116:117], v[188:189], v[116:117] op_sel_hi:[0,1]
	v_pk_fma_f32 v[128:129], v[4:5], v[116:117], v[96:97]
	v_add_f32_dpp v1, v1, v1 quad_perm:[1,0,3,2] row_mask:0xf bank_mask:0xf bound_ctrl:1
	s_nop 1
	v_add_f32_dpp v1, v1, v1 quad_perm:[2,3,0,1] row_mask:0xf bank_mask:0xf bound_ctrl:1
	s_nop 1
	v_add_f32_dpp v1, v1, v1 row_half_mirror row_mask:0xf bank_mask:0xf bound_ctrl:1
	s_nop 1
	v_add_f32_dpp v1, v1, v1 row_mirror row_mask:0xf bank_mask:0xf bound_ctrl:1
	v_mov_b32_e32 v118, v1
	s_nop 1
	v_permlane16_swap_b32_e32 v1, v118
	v_add_f32_e32 v1, v1, v118
	v_mov_b32_e32 v118, v1
	s_nop 1
	v_permlane32_swap_b32_e32 v1, v118
	v_add_f32_e32 v1, v1, v118
	v_fmamk_f32 v1, v1, 0x3a000000, v218
	v_cmp_gt_f32_e32 vcc, s30, v1
	v_mul_f32_e32 v118, 0x4f800000, v1
	s_nop 0
	v_cndmask_b32_e32 v1, v1, v118, vcc
	v_sqrt_f32_e32 v118, v1
	s_nop 0
	v_add_u32_e32 v119, -1, v118
	v_fma_f32 v122, -v119, v118, v1
	v_cmp_ge_f32_e64 s[40:41], 0, v122
	v_add_u32_e32 v122, 1, v118
	s_nop 0
	v_cndmask_b32_e64 v119, v118, v119, s[40:41]
	v_fma_f32 v118, -v122, v118, v1
	v_cmp_lt_f32_e64 s[40:41], 0, v118
	s_nop 1
	v_cndmask_b32_e64 v118, v119, v122, s[40:41]
	v_mul_f32_e32 v119, 0x37800000, v118
	v_cndmask_b32_e32 v118, v118, v119, vcc
	v_cmp_class_f32_e32 vcc, v1, v215
	s_nop 1
	v_cndmask_b32_e32 v1, v118, v1, vcc
	v_div_scale_f32 v118, s[0:1], v1, v1, 1.0
	v_rcp_f32_e32 v119, v118
	s_nop 0
	v_fma_f32 v122, -v118, v119, 1.0
	v_fmac_f32_e32 v119, v122, v119
	v_div_scale_f32 v122, vcc, 1.0, v1, 1.0
	v_mul_f32_e32 v123, v122, v119
	v_fma_f32 v126, -v118, v123, v122
	v_fmac_f32_e32 v123, v126, v119
	v_fma_f32 v118, -v118, v123, v122
	v_div_fmas_f32 v118, v118, v119, v123
	v_div_fixup_f32 v210, v118, v1, 1.0
	v_pk_mul_f32 v[118:119], v[188:189], v[168:169] op_sel_hi:[0,1]
	v_pk_fma_f32 v[126:127], v[2:3], v[118:119], v[94:95]
	v_pk_mul_f32 v[94:95], v[210:211], v[124:125] op_sel_hi:[0,1]
	v_pk_mul_f32 v[96:97], v[210:211], v[114:115] op_sel_hi:[0,1]
	v_pk_fma_f32 v[122:123], v[2:3], v[94:95], v[110:111]
	v_pk_mul_f32 v[94:95], v[188:189], v[170:171] op_sel_hi:[0,1]
	v_pk_fma_f32 v[124:125], v[4:5], v[96:97], v[112:113]
	v_pk_mul_f32 v[96:97], v[188:189], v[120:121] op_sel_hi:[0,1]
	v_pk_fma_f32 v[118:119], v[6:7], v[94:95], v[90:91]
	v_pk_mul_f32 v[90:91], v[210:211], v[190:191] op_sel_hi:[0,1]
	v_pk_fma_f32 v[120:121], v[8:9], v[96:97], v[92:93]
	v_pk_mul_f32 v[92:93], v[210:211], v[192:193] op_sel_hi:[0,1]
	v_pk_fma_f32 v[114:115], v[6:7], v[90:91], v[106:107]
	v_pk_mul_f32 v[90:91], v[188:189], v[172:173] op_sel_hi:[0,1]
	v_pk_fma_f32 v[116:117], v[8:9], v[92:93], v[108:109]
	v_pk_mul_f32 v[92:93], v[188:189], v[174:175] op_sel_hi:[0,1]
	v_pk_fma_f32 v[110:111], v[10:11], v[90:91], v[86:87]
	v_pk_mul_f32 v[86:87], v[210:211], v[194:195] op_sel_hi:[0,1]
	v_pk_fma_f32 v[112:113], v[12:13], v[92:93], v[88:89]
	v_pk_mul_f32 v[88:89], v[210:211], v[196:197] op_sel_hi:[0,1]
	v_pk_fma_f32 v[106:107], v[10:11], v[86:87], v[102:103]
	v_pk_mul_f32 v[86:87], v[188:189], v[176:177] op_sel_hi:[0,1]
	v_pk_fma_f32 v[108:109], v[12:13], v[88:89], v[104:105]
	v_pk_mul_f32 v[88:89], v[188:189], v[178:179] op_sel_hi:[0,1]
	v_pk_fma_f32 v[102:103], v[14:15], v[86:87], v[82:83]
	v_pk_mul_f32 v[82:83], v[210:211], v[198:199] op_sel_hi:[0,1]
	v_pk_fma_f32 v[104:105], v[16:17], v[88:89], v[84:85]
	v_pk_mul_f32 v[84:85], v[210:211], v[200:201] op_sel_hi:[0,1]
	v_pk_fma_f32 v[98:99], v[14:15], v[82:83], v[98:99]
	v_pk_mul_f32 v[82:83], v[188:189], v[180:181] op_sel_hi:[0,1]
	v_pk_fma_f32 v[100:101], v[16:17], v[84:85], v[100:101]
	v_pk_mul_f32 v[84:85], v[188:189], v[154:155] op_sel_hi:[0,1]
	v_pk_fma_f32 v[94:95], v[18:19], v[82:83], v[78:79]
	v_pk_mul_f32 v[78:79], v[210:211], v[202:203] op_sel_hi:[0,1]
	v_pk_fma_f32 v[96:97], v[20:21], v[84:85], v[80:81]
	v_pk_mul_f32 v[80:81], v[210:211], v[152:153] op_sel_hi:[0,1]
	v_pk_fma_f32 v[90:91], v[18:19], v[78:79], v[142:143]
	v_pk_mul_f32 v[78:79], v[188:189], v[182:183] op_sel_hi:[0,1]
	v_pk_fma_f32 v[92:93], v[20:21], v[80:81], v[144:145]
	v_pk_mul_f32 v[80:81], v[188:189], v[158:159] op_sel_hi:[0,1]
	v_pk_fma_f32 v[86:87], v[22:23], v[78:79], v[74:75]
	v_pk_mul_f32 v[74:75], v[210:211], v[204:205] op_sel_hi:[0,1]
	v_pk_fma_f32 v[88:89], v[24:25], v[80:81], v[76:77]
	v_pk_mul_f32 v[76:77], v[210:211], v[156:157] op_sel_hi:[0,1]
	v_pk_fma_f32 v[82:83], v[22:23], v[74:75], v[138:139]
	v_pk_mul_f32 v[74:75], v[188:189], v[184:185] op_sel_hi:[0,1]
	v_pk_fma_f32 v[84:85], v[24:25], v[76:77], v[140:141]
	v_pk_mul_f32 v[76:77], v[188:189], v[162:163] op_sel_hi:[0,1]
	v_pk_fma_f32 v[78:79], v[26:27], v[74:75], v[70:71]
	v_pk_mul_f32 v[70:71], v[210:211], v[206:207] op_sel_hi:[0,1]
	v_pk_fma_f32 v[80:81], v[28:29], v[76:77], v[72:73]
	v_pk_mul_f32 v[72:73], v[210:211], v[160:161] op_sel_hi:[0,1]
	v_pk_fma_f32 v[74:75], v[26:27], v[70:71], v[134:135]
	v_pk_mul_f32 v[70:71], v[188:189], v[186:187] op_sel_hi:[0,1]
	v_pk_fma_f32 v[76:77], v[28:29], v[72:73], v[136:137]
	v_pk_mul_f32 v[72:73], v[188:189], v[166:167] op_sel_hi:[0,1]
	v_pk_fma_f32 v[70:71], v[30:31], v[70:71], v[66:67]
	v_pk_mul_f32 v[66:67], v[210:211], v[208:209] op_sel_hi:[0,1]
	v_pk_fma_f32 v[72:73], v[32:33], v[72:73], v[68:69]
	v_pk_mul_f32 v[68:69], v[210:211], v[164:165] op_sel_hi:[0,1]
; template <int MODE> ...
;     ...
;         if (MODE != 0)
; #pragma unroll
;         for (int rr = 0; rr < RPW; ++rr) { float* xo = xres + (size_t)(m + rr) * DM + lane * 4;
; #pragma unroll
;             for (int k = 0; k < 8; ++k) *(f32x4*)(xo + k * 256) = xv[rr][k]; }
;         if (MODE <= 1) {
;             float rstd[RPW];
; #pragma unroll
;             for (int rr = 0; rr < RPW; ++rr) { float s = 0.f;
; #pragma unroll
;                 for (int k = 0; k < 8; ++k) s += (xv[rr][k][0] * xv[rr][k][0] + xv[rr][k][1] * xv[rr][k][1]) + (xv[rr][k][2] * xv[rr][k][2] + xv[rr][k][3] * xv[rr][k][3]);
;                 rstd[rr] = 1.0f / sqrtf(wave_sum(s) * (1.f / DM) + RMS_EPS); }
	v_pk_fma_f32 v[66:67], v[30:31], v[66:67], v[130:131]
	v_lshl_add_u64 v[130:131], s[78:79], 0, v[146:147]
	v_pk_fma_f32 v[68:69], v[32:33], v[68:69], v[132:133]
	v_add_co_u32_e32 v132, vcc, s19, v130
	global_store_dwordx4 v[130:131], v[126:129], off sc0 sc1
	global_store_dwordx4 v[130:131], v[118:121], off offset:1024 sc0 sc1
	global_store_dwordx4 v[130:131], v[110:113], off offset:2048 sc0 sc1
	global_store_dwordx4 v[130:131], v[102:105], off offset:3072 sc0 sc1
	v_addc_co_u32_e32 v133, vcc, 0, v131, vcc
	v_add_co_u32_e32 v134, vcc, s31, v130
	v_mul_f32_e32 v1, v127, v127
	s_nop 0
	v_addc_co_u32_e32 v135, vcc, 0, v131, vcc
	v_add_co_u32_e32 v130, vcc, s33, v130
	global_store_dwordx4 v[134:135], v[94:97], off offset:-4096 sc0 sc1
	global_store_dwordx4 v[132:133], v[86:89], off offset:1024 sc0 sc1
	global_store_dwordx4 v[132:133], v[78:81], off offset:2048 sc0 sc1
	global_store_dwordx4 v[132:133], v[70:73], off offset:3072 sc0 sc1
	global_store_dwordx4 v[134:135], v[122:125], off sc0 sc1
	global_store_dwordx4 v[134:135], v[114:117], off offset:1024 sc0 sc1
	global_store_dwordx4 v[134:135], v[106:109], off offset:2048 sc0 sc1
	global_store_dwordx4 v[134:135], v[98:101], off offset:3072 sc0 sc1
	v_addc_co_u32_e32 v131, vcc, 0, v131, vcc
	global_store_dwordx4 v[130:131], v[90:93], off sc0 sc1
	global_store_dwordx4 v[130:131], v[82:85], off offset:1024 sc0 sc1
	global_store_dwordx4 v[130:131], v[74:77], off offset:2048 sc0 sc1
	global_store_dwordx4 v[130:131], v[66:69], off offset:3072 sc0 sc1
	v_mul_f32_e32 v130, v129, v129
	v_fmac_f32_e32 v1, v126, v126
	v_fmac_f32_e32 v130, v128, v128
	v_add_f32_e32 v1, v1, v130
	v_mul_f32_e32 v130, v119, v119
	v_mul_f32_e32 v131, v121, v121
	v_fmac_f32_e32 v130, v118, v118
	v_fmac_f32_e32 v131, v120, v120
	v_add_f32_e32 v130, v130, v131
	v_add_f32_e32 v1, v1, v130
	v_mul_f32_e32 v130, v111, v111
	v_mul_f32_e32 v131, v113, v113
	v_fmac_f32_e32 v130, v110, v110
	v_fmac_f32_e32 v131, v112, v112
	v_add_f32_e32 v130, v130, v131
	v_add_f32_e32 v1, v130, v1
	v_mul_f32_e32 v130, v103, v103
	v_mul_f32_e32 v131, v105, v105
	v_fmac_f32_e32 v130, v102, v102
	v_fmac_f32_e32 v131, v104, v104
	v_add_f32_e32 v130, v130, v131
	v_add_f32_e32 v1, v130, v1
	v_mul_f32_e32 v130, v95, v95
	v_mul_f32_e32 v131, v97, v97
	v_fmac_f32_e32 v130, v94, v94
	v_fmac_f32_e32 v131, v96, v96
	v_add_f32_e32 v130, v130, v131
	v_add_f32_e32 v1, v130, v1
	v_mul_f32_e32 v130, v87, v87
	v_mul_f32_e32 v131, v89, v89
	v_fmac_f32_e32 v130, v86, v86
	v_fmac_f32_e32 v131, v88, v88
	v_add_f32_e32 v130, v130, v131
	v_add_f32_e32 v1, v130, v1
	v_mul_f32_e32 v130, v79, v79
	v_mul_f32_e32 v131, v81, v81
	v_fmac_f32_e32 v130, v78, v78
	v_fmac_f32_e32 v131, v80, v80
	v_add_f32_e32 v130, v130, v131
	v_add_f32_e32 v1, v130, v1
	v_mul_f32_e32 v130, v71, v71
	v_mul_f32_e32 v131, v73, v73
	v_fmac_f32_e32 v130, v70, v70
	v_fmac_f32_e32 v131, v72, v72
	v_add_f32_e32 v130, v130, v131
	v_add_f32_e32 v1, v130, v1
	s_add_u32 s78, s78, s26
	s_addc_u32 s79, s79, s27
	v_add_f32_dpp v1, v1, v1 quad_perm:[1,0,3,2] row_mask:0xf bank_mask:0xf bound_ctrl:1
	s_add_u32 s64, s64, s26
	s_addc_u32 s65, s65, s27
	v_add_f32_dpp v1, v1, v1 quad_perm:[2,3,0,1] row_mask:0xf bank_mask:0xf bound_ctrl:1
	s_cmpk_gt_i32 s42, 0x3fff
	s_nop 0
	v_add_f32_dpp v1, v1, v1 row_half_mirror row_mask:0xf bank_mask:0xf bound_ctrl:1
	s_nop 1
	v_add_f32_dpp v1, v1, v1 row_mirror row_mask:0xf bank_mask:0xf bound_ctrl:1
	v_mov_b32_e32 v130, v1
	s_nop 1
	v_permlane16_swap_b32_e32 v1, v130
	v_add_f32_e32 v1, v1, v130
	v_mov_b32_e32 v130, v1
	s_nop 1
	v_permlane32_swap_b32_e32 v1, v130
	v_add_f32_e32 v1, v1, v130
	v_fmamk_f32 v1, v1, 0x3a000000, v218
	v_cmp_gt_f32_e32 vcc, s30, v1
	v_mul_f32_e32 v130, 0x4f800000, v1
	s_nop 0
	v_cndmask_b32_e32 v1, v1, v130, vcc
	v_sqrt_f32_e32 v130, v1
	s_nop 0
	v_add_u32_e32 v131, -1, v130
	v_fma_f32 v132, -v131, v130, v1
	v_cmp_ge_f32_e64 s[40:41], 0, v132
	v_add_u32_e32 v132, 1, v130
	s_nop 0
	v_cndmask_b32_e64 v131, v130, v131, s[40:41]
	v_fma_f32 v130, -v132, v130, v1
	v_cmp_lt_f32_e64 s[40:41], 0, v130
	s_nop 1
	v_cndmask_b32_e64 v130, v131, v132, s[40:41]
	v_mul_f32_e32 v131, 0x37800000, v130
	v_cndmask_b32_e32 v130, v130, v131, vcc
	v_cmp_class_f32_e32 vcc, v1, v215
	s_nop 1
	v_cndmask_b32_e32 v1, v130, v1, vcc
	v_div_scale_f32 v130, s[0:1], v1, v1, 1.0
	v_rcp_f32_e32 v131, v130
	s_nop 0
	v_fma_f32 v132, -v130, v131, 1.0
	v_fmac_f32_e32 v131, v132, v131
	v_div_scale_f32 v132, vcc, 1.0, v1, 1.0
	v_mul_f32_e32 v133, v132, v131
	v_fma_f32 v134, -v130, v133, v132
	v_fmac_f32_e32 v133, v134, v131
	v_fma_f32 v130, -v130, v133, v132
	v_div_fmas_f32 v130, v130, v131, v133
	v_div_fixup_f32 v130, v130, v1, 1.0
	v_mul_f32_e32 v1, v123, v123
	v_mul_f32_e32 v131, v125, v125
	v_fmac_f32_e32 v1, v122, v122
	v_fmac_f32_e32 v131, v124, v124
	v_add_f32_e32 v1, v1, v131
	v_mul_f32_e32 v131, v115, v115
	v_mul_f32_e32 v132, v117, v117
	v_fmac_f32_e32 v131, v114, v114
	v_fmac_f32_e32 v132, v116, v116
	v_add_f32_e32 v131, v131, v132
	v_add_f32_e32 v1, v1, v131
	v_mul_f32_e32 v131, v107, v107
	v_mul_f32_e32 v132, v109, v109
	v_fmac_f32_e32 v131, v106, v106
	v_fmac_f32_e32 v132, v108, v108
	v_add_f32_e32 v131, v131, v132
	v_add_f32_e32 v1, v131, v1
	v_mul_f32_e32 v131, v99, v99
	v_mul_f32_e32 v132, v101, v101
	v_fmac_f32_e32 v131, v98, v98
	v_fmac_f32_e32 v132, v100, v100
	v_add_f32_e32 v131, v131, v132
	v_add_f32_e32 v1, v131, v1
	v_mul_f32_e32 v131, v91, v91
	v_mul_f32_e32 v132, v93, v93
	v_fmac_f32_e32 v131, v90, v90
	v_fmac_f32_e32 v132, v92, v92
	v_add_f32_e32 v131, v131, v132
	v_add_f32_e32 v1, v131, v1
	v_mul_f32_e32 v131, v83, v83
	v_mul_f32_e32 v132, v85, v85
	v_fmac_f32_e32 v131, v82, v82
; __device__ __forceinline__ unsigned pk2(float lo, float hi) { return f2bf(lo) | (f2bf(hi) << 16); }
; template <int MODE> ...
;     ...
;             for (int rr = 0; rr < RPW; ++rr) { float s = 0.f;
; #pragma unroll
;                 for (int k = 0; k < 8; ++k) s += (xv[rr][k][0] * xv[rr][k][0] + xv[rr][k][1] * xv[rr][k][1]) + (xv[rr][k][2] * xv[rr][k][2] + xv[rr][k][3] * xv[rr][k][3]);
;                 rstd[rr] = 1.0f / sqrtf(wave_sum(s) * (1.f / DM) + RMS_EPS); }
; #pragma unroll
;             for (int k = 0; k < 8; ++k) { const f32x4 g = *(const f32x4*)(gpre + k * 256 + lane * 4);
; #pragma unroll
;                 for (int rr = 0; rr < RPW; ++rr) { const f32x4 a = xv[rr][k] * rstd[rr] * g;
;                     v2u o; o.x = pk2(a[0], a[1]); o.y = pk2(a[2], a[3]);
;                     *(v2u*)(h + ((size_t)(k * 4 + (lane >> 4)) * M_TOK + (m + rr)) * 64 + (lane & 15) * 4) = o; } }
	v_fmac_f32_e32 v132, v84, v84
	v_add_f32_e32 v131, v131, v132
	v_add_f32_e32 v1, v131, v1
	v_mul_f32_e32 v131, v75, v75
	v_mul_f32_e32 v132, v77, v77
	v_fmac_f32_e32 v131, v74, v74
	v_fmac_f32_e32 v132, v76, v76
	v_add_f32_e32 v131, v131, v132
	v_add_f32_e32 v1, v131, v1
	v_mul_f32_e32 v131, v67, v67
	v_mul_f32_e32 v132, v69, v69
	v_fmac_f32_e32 v131, v66, v66
	v_fmac_f32_e32 v132, v68, v68
	v_add_f32_e32 v131, v131, v132
	v_add_f32_e32 v1, v131, v1
	s_nop 1
	v_add_f32_dpp v1, v1, v1 quad_perm:[1,0,3,2] row_mask:0xf bank_mask:0xf bound_ctrl:1
	s_nop 1
	v_add_f32_dpp v1, v1, v1 quad_perm:[2,3,0,1] row_mask:0xf bank_mask:0xf bound_ctrl:1
	s_nop 1
	v_add_f32_dpp v1, v1, v1 row_half_mirror row_mask:0xf bank_mask:0xf bound_ctrl:1
	s_nop 1
	v_add_f32_dpp v1, v1, v1 row_mirror row_mask:0xf bank_mask:0xf bound_ctrl:1
	v_mov_b32_e32 v131, v1
	s_nop 1
	v_permlane16_swap_b32_e32 v1, v131
	v_add_f32_e32 v1, v1, v131
	v_mov_b32_e32 v131, v1
	s_nop 1
	v_permlane32_swap_b32_e32 v1, v131
	v_add_f32_e32 v1, v1, v131
	v_fmamk_f32 v1, v1, 0x3a000000, v218
	v_cmp_gt_f32_e32 vcc, s30, v1
	v_mul_f32_e32 v131, 0x4f800000, v1
	s_nop 0
	v_cndmask_b32_e32 v1, v1, v131, vcc
	v_sqrt_f32_e32 v131, v1
	s_nop 0
	v_add_u32_e32 v132, -1, v131
	v_fma_f32 v133, -v132, v131, v1
	v_cmp_ge_f32_e64 s[40:41], 0, v133
	v_add_u32_e32 v133, 1, v131
	s_nop 0
	v_cndmask_b32_e64 v132, v131, v132, s[40:41]
	v_fma_f32 v131, -v133, v131, v1
	v_cmp_lt_f32_e64 s[40:41], 0, v131
	s_nop 1
	v_cndmask_b32_e64 v131, v132, v133, s[40:41]
	v_mul_f32_e32 v132, 0x37800000, v131
	v_cndmask_b32_e32 v131, v131, v132, vcc
	v_cmp_class_f32_e32 vcc, v1, v215
	s_nop 1
	v_cndmask_b32_e32 v1, v131, v1, vcc
	v_div_scale_f32 v131, s[0:1], v1, v1, 1.0
	v_rcp_f32_e32 v132, v131
	s_mov_b32 s0, 0x4800000
	v_fma_f32 v133, -v131, v132, 1.0
	v_fmac_f32_e32 v132, v133, v132
	v_div_scale_f32 v133, vcc, 1.0, v1, 1.0
	v_mul_f32_e32 v134, v133, v132
	v_fma_f32 v135, -v131, v134, v133
	v_fmac_f32_e32 v134, v135, v132
	v_fma_f32 v131, -v131, v134, v133
	v_div_fmas_f32 v131, v131, v132, v134
	v_pk_mul_f32 v[126:127], v[126:127], v[130:131] op_sel_hi:[1,0]
	v_div_fixup_f32 v132, v131, v1, 1.0
	v_pk_mul_f32 v[126:127], v[46:47], v[126:127]
	v_pk_mul_f32 v[128:129], v[128:129], v[130:131] op_sel_hi:[1,0]
	v_bfe_u32 v1, v126, 16, 1
	v_add3_u32 v1, v126, v1, s63
	v_bfe_u32 v126, v127, 16, 1
	v_pk_mul_f32 v[128:129], v[48:49], v[128:129]
	v_lshrrev_b32_e32 v1, 16, v1
	v_add3_u32 v126, v127, v126, s63
	v_and_or_b32 v126, v126, s60, v1
	v_bfe_u32 v1, v128, 16, 1
	v_add3_u32 v1, v128, v1, s63
	v_bfe_u32 v127, v129, 16, 1
	v_pk_mul_f32 v[122:123], v[122:123], v[132:133] op_sel_hi:[1,0]
	v_lshrrev_b32_e32 v1, 16, v1
	v_add3_u32 v127, v129, v127, s63
	v_pk_mul_f32 v[122:123], v[46:47], v[122:123]
	v_and_or_b32 v127, v127, s60, v1
	v_bfe_u32 v1, v122, 16, 1
	v_pk_mul_f32 v[124:125], v[124:125], v[132:133] op_sel_hi:[1,0]
	v_add3_u32 v1, v122, v1, s63
	v_bfe_u32 v122, v123, 16, 1
	v_pk_mul_f32 v[124:125], v[48:49], v[124:125]
	v_lshrrev_b32_e32 v1, 16, v1
	v_add3_u32 v122, v123, v122, s63
	v_and_or_b32 v122, v122, s60, v1
	v_bfe_u32 v1, v124, 16, 1
	v_add3_u32 v1, v124, v1, s63
	v_bfe_u32 v123, v125, 16, 1
	v_pk_mul_f32 v[118:119], v[118:119], v[130:131] op_sel_hi:[1,0]
	v_lshrrev_b32_e32 v1, 16, v1
	v_add3_u32 v123, v125, v123, s63
	v_pk_mul_f32 v[118:119], v[34:35], v[118:119]
	v_and_or_b32 v123, v123, s60, v1
	v_bfe_u32 v1, v118, 16, 1
	v_pk_mul_f32 v[120:121], v[120:121], v[130:131] op_sel_hi:[1,0]
	v_add3_u32 v1, v118, v1, s63
	v_bfe_u32 v118, v119, 16, 1
	v_pk_mul_f32 v[120:121], v[36:37], v[120:121]
	v_lshrrev_b32_e32 v1, 16, v1
	v_add3_u32 v118, v119, v118, s63
	v_and_or_b32 v118, v118, s60, v1
	v_bfe_u32 v1, v120, 16, 1
	v_add3_u32 v1, v120, v1, s63
	v_bfe_u32 v119, v121, 16, 1
	v_pk_mul_f32 v[114:115], v[114:115], v[132:133] op_sel_hi:[1,0]
	v_lshrrev_b32_e32 v1, 16, v1
	v_add3_u32 v119, v121, v119, s63
	v_pk_mul_f32 v[114:115], v[34:35], v[114:115]
	v_and_or_b32 v119, v119, s60, v1
	v_bfe_u32 v1, v114, 16, 1
	v_pk_mul_f32 v[116:117], v[116:117], v[132:133] op_sel_hi:[1,0]
	v_add3_u32 v1, v114, v1, s63
	v_bfe_u32 v114, v115, 16, 1
	v_pk_mul_f32 v[116:117], v[36:37], v[116:117]
	v_lshrrev_b32_e32 v1, 16, v1
	v_add3_u32 v114, v115, v114, s63
	v_and_or_b32 v114, v114, s60, v1
	v_bfe_u32 v1, v116, 16, 1
	v_add3_u32 v1, v116, v1, s63
	v_bfe_u32 v115, v117, 16, 1
	v_pk_mul_f32 v[110:111], v[110:111], v[130:131] op_sel_hi:[1,0]
	v_lshrrev_b32_e32 v1, 16, v1
	v_add3_u32 v115, v117, v115, s63
	v_pk_mul_f32 v[110:111], v[38:39], v[110:111]
	v_and_or_b32 v115, v115, s60, v1
	v_bfe_u32 v1, v110, 16, 1
	v_pk_mul_f32 v[112:113], v[112:113], v[130:131] op_sel_hi:[1,0]
	v_add3_u32 v1, v110, v1, s63
	v_bfe_u32 v110, v111, 16, 1
	v_pk_mul_f32 v[112:113], v[40:41], v[112:113]
	v_lshrrev_b32_e32 v1, 16, v1
	v_add3_u32 v110, v111, v110, s63
	v_and_or_b32 v110, v110, s60, v1
	v_bfe_u32 v1, v112, 16, 1
	v_add3_u32 v1, v112, v1, s63
	v_bfe_u32 v111, v113, 16, 1
	v_pk_mul_f32 v[106:107], v[106:107], v[132:133] op_sel_hi:[1,0]
	v_lshrrev_b32_e32 v1, 16, v1
	v_add3_u32 v111, v113, v111, s63
	v_pk_mul_f32 v[106:107], v[38:39], v[106:107]
	v_and_or_b32 v111, v111, s60, v1
	v_bfe_u32 v1, v106, 16, 1
	v_pk_mul_f32 v[108:109], v[108:109], v[132:133] op_sel_hi:[1,0]
	v_add3_u32 v1, v106, v1, s63
	v_bfe_u32 v106, v107, 16, 1
	v_pk_mul_f32 v[108:109], v[40:41], v[108:109]
	v_lshrrev_b32_e32 v1, 16, v1
	v_add3_u32 v106, v107, v106, s63
	v_and_or_b32 v106, v106, s60, v1
	v_bfe_u32 v1, v108, 16, 1
	v_add3_u32 v1, v108, v1, s63
	v_bfe_u32 v107, v109, 16, 1
	v_pk_mul_f32 v[102:103], v[102:103], v[130:131] op_sel_hi:[1,0]
	v_lshrrev_b32_e32 v1, 16, v1
; __device__ __forceinline__ unsigned pk2(float lo, float hi) { return f2bf(lo) | (f2bf(hi) << 16); }
; template <int MODE> ...
;     ...
; #pragma unroll
;             for (int k = 0; k < 8; ++k) { const f32x4 g = *(const f32x4*)(gpre + k * 256 + lane * 4);
; #pragma unroll
;                 for (int rr = 0; rr < RPW; ++rr) { const f32x4 a = xv[rr][k] * rstd[rr] * g;
;                     v2u o; o.x = pk2(a[0], a[1]); o.y = pk2(a[2], a[3]);
;                     *(v2u*)(h + ((size_t)(k * 4 + (lane >> 4)) * M_TOK + (m + rr)) * 64 + (lane & 15) * 4) = o; } }
	v_add3_u32 v107, v109, v107, s63
	v_pk_mul_f32 v[102:103], v[42:43], v[102:103]
	v_and_or_b32 v107, v107, s60, v1
	v_bfe_u32 v1, v102, 16, 1
	v_pk_mul_f32 v[104:105], v[104:105], v[130:131] op_sel_hi:[1,0]
	v_add3_u32 v1, v102, v1, s63
	v_bfe_u32 v102, v103, 16, 1
	v_pk_mul_f32 v[104:105], v[44:45], v[104:105]
	v_lshrrev_b32_e32 v1, 16, v1
	v_add3_u32 v102, v103, v102, s63
	v_and_or_b32 v102, v102, s60, v1
	v_bfe_u32 v1, v104, 16, 1
	v_add3_u32 v1, v104, v1, s63
	v_bfe_u32 v103, v105, 16, 1
	v_pk_mul_f32 v[98:99], v[98:99], v[132:133] op_sel_hi:[1,0]
	v_lshrrev_b32_e32 v1, 16, v1
	v_add3_u32 v103, v105, v103, s63
	v_pk_mul_f32 v[98:99], v[42:43], v[98:99]
	v_and_or_b32 v103, v103, s60, v1
	v_bfe_u32 v1, v98, 16, 1
	v_pk_mul_f32 v[100:101], v[100:101], v[132:133] op_sel_hi:[1,0]
	v_add3_u32 v1, v98, v1, s63
	v_bfe_u32 v98, v99, 16, 1
	v_pk_mul_f32 v[100:101], v[44:45], v[100:101]
	v_lshrrev_b32_e32 v1, 16, v1
	v_add3_u32 v98, v99, v98, s63
	v_and_or_b32 v98, v98, s60, v1
	v_bfe_u32 v1, v100, 16, 1
	v_add3_u32 v1, v100, v1, s63
	v_bfe_u32 v99, v101, 16, 1
	v_pk_mul_f32 v[94:95], v[94:95], v[130:131] op_sel_hi:[1,0]
	v_lshrrev_b32_e32 v1, 16, v1
	v_add3_u32 v99, v101, v99, s63
	v_pk_mul_f32 v[94:95], v[50:51], v[94:95]
	v_and_or_b32 v99, v99, s60, v1
	v_bfe_u32 v1, v94, 16, 1
	v_pk_mul_f32 v[96:97], v[96:97], v[130:131] op_sel_hi:[1,0]
	v_add3_u32 v1, v94, v1, s63
	v_bfe_u32 v94, v95, 16, 1
	v_pk_mul_f32 v[96:97], v[52:53], v[96:97]
	v_lshrrev_b32_e32 v1, 16, v1
	v_add3_u32 v94, v95, v94, s63
	v_and_or_b32 v94, v94, s60, v1
	v_bfe_u32 v1, v96, 16, 1
	v_add3_u32 v1, v96, v1, s63
	v_bfe_u32 v95, v97, 16, 1
	v_pk_mul_f32 v[90:91], v[90:91], v[132:133] op_sel_hi:[1,0]
	v_lshrrev_b32_e32 v1, 16, v1
	v_add3_u32 v95, v97, v95, s63
	v_pk_mul_f32 v[90:91], v[50:51], v[90:91]
	v_and_or_b32 v95, v95, s60, v1
	v_bfe_u32 v1, v90, 16, 1
	v_pk_mul_f32 v[92:93], v[92:93], v[132:133] op_sel_hi:[1,0]
	v_add3_u32 v1, v90, v1, s63
	v_bfe_u32 v90, v91, 16, 1
	v_pk_mul_f32 v[92:93], v[52:53], v[92:93]
	v_lshrrev_b32_e32 v1, 16, v1
	v_add3_u32 v90, v91, v90, s63
	v_and_or_b32 v90, v90, s60, v1
	v_bfe_u32 v1, v92, 16, 1
	v_add3_u32 v1, v92, v1, s63
	v_bfe_u32 v91, v93, 16, 1
	v_pk_mul_f32 v[86:87], v[86:87], v[130:131] op_sel_hi:[1,0]
	v_lshrrev_b32_e32 v1, 16, v1
	v_add3_u32 v91, v93, v91, s63
	v_pk_mul_f32 v[86:87], v[54:55], v[86:87]
	v_and_or_b32 v91, v91, s60, v1
	v_bfe_u32 v1, v86, 16, 1
	v_pk_mul_f32 v[88:89], v[88:89], v[130:131] op_sel_hi:[1,0]
	v_add3_u32 v1, v86, v1, s63
	v_bfe_u32 v86, v87, 16, 1
	v_pk_mul_f32 v[88:89], v[56:57], v[88:89]
	v_lshrrev_b32_e32 v1, 16, v1
	v_add3_u32 v86, v87, v86, s63
	v_and_or_b32 v86, v86, s60, v1
	v_bfe_u32 v1, v88, 16, 1
	v_add3_u32 v1, v88, v1, s63
	v_bfe_u32 v87, v89, 16, 1
	v_pk_mul_f32 v[82:83], v[82:83], v[132:133] op_sel_hi:[1,0]
	v_lshrrev_b32_e32 v1, 16, v1
	v_add3_u32 v87, v89, v87, s63
	v_pk_mul_f32 v[82:83], v[54:55], v[82:83]
	v_and_or_b32 v87, v87, s60, v1
	v_bfe_u32 v1, v82, 16, 1
	v_pk_mul_f32 v[84:85], v[84:85], v[132:133] op_sel_hi:[1,0]
	v_add3_u32 v1, v82, v1, s63
	v_bfe_u32 v82, v83, 16, 1
	v_pk_mul_f32 v[84:85], v[56:57], v[84:85]
	v_lshrrev_b32_e32 v1, 16, v1
	v_add3_u32 v82, v83, v82, s63
	v_and_or_b32 v82, v82, s60, v1
	v_bfe_u32 v1, v84, 16, 1
	v_add3_u32 v1, v84, v1, s63
	v_bfe_u32 v83, v85, 16, 1
	v_pk_mul_f32 v[78:79], v[78:79], v[130:131] op_sel_hi:[1,0]
	v_lshrrev_b32_e32 v1, 16, v1
	v_add3_u32 v83, v85, v83, s63
	v_pk_mul_f32 v[78:79], v[58:59], v[78:79]
	v_and_or_b32 v83, v83, s60, v1
	v_bfe_u32 v1, v78, 16, 1
	v_pk_mul_f32 v[80:81], v[80:81], v[130:131] op_sel_hi:[1,0]
	v_add3_u32 v1, v78, v1, s63
	v_bfe_u32 v78, v79, 16, 1
	v_pk_mul_f32 v[80:81], v[60:61], v[80:81]
	v_lshrrev_b32_e32 v1, 16, v1
; __device__ __forceinline__ unsigned pk2(float lo, float hi) { return f2bf(lo) | (f2bf(hi) << 16); }
; template <int MODE> ...
;     ...
; #pragma unroll
;             for (int k = 0; k < 8; ++k) { const f32x4 g = *(const f32x4*)(gpre + k * 256 + lane * 4);
; #pragma unroll
;                 for (int rr = 0; rr < RPW; ++rr) { const f32x4 a = xv[rr][k] * rstd[rr] * g;
;                     v2u o; o.x = pk2(a[0], a[1]); o.y = pk2(a[2], a[3]);
;                     *(v2u*)(h + ((size_t)(k * 4 + (lane >> 4)) * M_TOK + (m + rr)) * 64 + (lane & 15) * 4) = o; } }
	v_add3_u32 v78, v79, v78, s63
	v_and_or_b32 v78, v78, s60, v1
	v_bfe_u32 v1, v80, 16, 1
	v_add3_u32 v1, v80, v1, s63
	v_bfe_u32 v79, v81, 16, 1
	v_pk_mul_f32 v[74:75], v[74:75], v[132:133] op_sel_hi:[1,0]
	v_lshrrev_b32_e32 v1, 16, v1
	v_add3_u32 v79, v81, v79, s63
	v_pk_mul_f32 v[74:75], v[58:59], v[74:75]
	v_and_or_b32 v79, v79, s60, v1
	v_bfe_u32 v1, v74, 16, 1
	v_pk_mul_f32 v[76:77], v[76:77], v[132:133] op_sel_hi:[1,0]
	v_add3_u32 v1, v74, v1, s63
	v_bfe_u32 v74, v75, 16, 1
	v_lshl_add_u64 v[128:129], v[148:149], 0, s[46:47]
	v_pk_mul_f32 v[76:77], v[60:61], v[76:77]
	v_lshrrev_b32_e32 v1, 16, v1
	v_add3_u32 v74, v75, v74, s63
	v_add_co_u32_e32 v134, vcc, s0, v128
	v_and_or_b32 v74, v74, s60, v1
	v_bfe_u32 v1, v76, 16, 1
	v_addc_co_u32_e32 v135, vcc, 0, v129, vcc
	s_mov_b32 s0, 0x5000000
	v_add3_u32 v1, v76, v1, s63
	v_bfe_u32 v75, v77, 16, 1
	v_pk_mul_f32 v[70:71], v[70:71], v[130:131] op_sel_hi:[1,0]
	v_add_co_u32_e32 v120, vcc, s0, v128
	v_lshrrev_b32_e32 v1, 16, v1
	v_add3_u32 v75, v77, v75, s63
	v_pk_mul_f32 v[70:71], v[62:63], v[70:71]
	v_addc_co_u32_e32 v121, vcc, 0, v129, vcc
	s_mov_b32 s0, 0x5800000
	v_and_or_b32 v75, v75, s60, v1
	v_bfe_u32 v1, v70, 16, 1
	v_add_co_u32_e32 v112, vcc, s0, v128
	v_pk_mul_f32 v[72:73], v[72:73], v[130:131] op_sel_hi:[1,0]
	v_add3_u32 v1, v70, v1, s63
	v_bfe_u32 v70, v71, 16, 1
	v_addc_co_u32_e32 v113, vcc, 0, v129, vcc
	s_mov_b32 s0, 0x6000000
	v_pk_mul_f32 v[72:73], v[64:65], v[72:73]
	v_lshrrev_b32_e32 v1, 16, v1
	v_add3_u32 v70, v71, v70, s63
	v_add_co_u32_e32 v104, vcc, s0, v128
	v_and_or_b32 v70, v70, s60, v1
	v_bfe_u32 v1, v72, 16, 1
	v_addc_co_u32_e32 v105, vcc, 0, v129, vcc
	s_mov_b32 s0, 0x6800000
	v_add3_u32 v1, v72, v1, s63
	v_bfe_u32 v71, v73, 16, 1
	v_pk_mul_f32 v[66:67], v[66:67], v[132:133] op_sel_hi:[1,0]
	v_add_co_u32_e32 v96, vcc, s0, v128
	v_lshrrev_b32_e32 v1, 16, v1
	v_add3_u32 v71, v73, v71, s63
	v_pk_mul_f32 v[66:67], v[62:63], v[66:67]
	v_addc_co_u32_e32 v97, vcc, 0, v129, vcc
	s_mov_b32 s0, 0x7000000
	v_and_or_b32 v71, v71, s60, v1
	v_bfe_u32 v1, v66, 16, 1
	v_add_co_u32_e32 v88, vcc, s0, v128
	v_pk_mul_f32 v[68:69], v[68:69], v[132:133] op_sel_hi:[1,0]
	v_add3_u32 v1, v66, v1, s63
	v_bfe_u32 v66, v67, 16, 1
	v_addc_co_u32_e32 v89, vcc, 0, v129, vcc
	s_mov_b32 s0, 0x7800000
	v_pk_mul_f32 v[68:69], v[64:65], v[68:69]
	v_lshrrev_b32_e32 v1, 16, v1
	v_add3_u32 v66, v67, v66, s63
	v_add_co_u32_e32 v80, vcc, s0, v128
	v_and_or_b32 v66, v66, s60, v1
	v_bfe_u32 v1, v68, 16, 1
	v_addc_co_u32_e32 v81, vcc, 0, v129, vcc
	s_brev_b32 s0, 16
	v_add3_u32 v1, v68, v1, s63
	v_bfe_u32 v67, v69, 16, 1
	v_add_co_u32_e32 v72, vcc, s0, v128
	v_lshrrev_b32_e32 v1, 16, v1
	v_add3_u32 v67, v69, v67, s63
	v_addc_co_u32_e32 v73, vcc, 0, v129, vcc
	v_and_or_b32 v67, v67, s60, v1
	v_lshl_add_u64 v[148:149], v[148:149], 0, s[20:21]
	global_store_dwordx2 v[134:135], v[126:127], off
	global_store_dwordx2 v[134:135], v[122:123], off offset:128
	global_store_dwordx2 v[120:121], v[118:119], off
	global_store_dwordx2 v[120:121], v[114:115], off offset:128
	global_store_dwordx2 v[112:113], v[110:111], off
	global_store_dwordx2 v[112:113], v[106:107], off offset:128
	global_store_dwordx2 v[104:105], v[102:103], off
	global_store_dwordx2 v[104:105], v[98:99], off offset:128
	global_store_dwordx2 v[96:97], v[94:95], off
	global_store_dwordx2 v[96:97], v[90:91], off offset:128
	global_store_dwordx2 v[88:89], v[86:87], off
	global_store_dwordx2 v[88:89], v[82:83], off offset:128
	global_store_dwordx2 v[80:81], v[78:79], off
	global_store_dwordx2 v[80:81], v[74:75], off offset:128
	global_store_dwordx2 v[72:73], v[70:71], off
	global_store_dwordx2 v[72:73], v[66:67], off offset:128
	s_cbranch_scc0 .LBB0_225

; __device__ __forceinline__ float bf2f(unsigned h) { return __uint_as_float(h << 16); }
; template <int MODE> ...
;     ...
; #pragma unroll
;         for (int rr = 0; rr < RPW; ++rr) {
;             const float* xr = ((MODE == 0 || xin != nullptr) ? xin : xres) + (size_t)(m + rr) * DM + lane * 4;
; #pragma unroll
;             for (int k = 0; k < 8; ++k) xv[rr][k] = *(const f32x4*)(xr + k * 256);
;             if (MODE >= 1) { const bf16_t* yr = y + (size_t)(m + rr) * 256 + lane * 4;
; #pragma unroll
;                 for (int k = 0; k < 8; ++k) yy[rr][k] = *(const v2u*)(yr + (size_t)k * ((size_t)M_TOK * 256)); }
;         }
;         if (MODE >= 1) {
;             float rstd[RPW];
; #pragma unroll
;             for (int rr = 0; rr < RPW; ++rr) { float s = 0.f;
; #pragma unroll
;                 for (int k = 0; k < 8; ++k)
; #pragma unroll
;                     for (int e = 0; e < 2; ++e) { const float a = bf2f(yy[rr][k][e] & 0xffffu), b = bf2f(yy[rr][k][e] >> 16); s += a * a + b * b; }
;                 rstd[rr] = 1.0f / sqrtf(wave_sum(s) * (1.f / DM) + RMS_EPS); }
.LBB0_230:
	v_add_co_u32_e32 v104, vcc, 0xffffe000, v100
	s_add_i32 s30, s30, s6
	s_nop 0
	v_addc_co_u32_e32 v105, vcc, -1, v101, vcc
	v_add_co_u32_e32 v102, vcc, 0xfffff000, v100
	global_load_dwordx4 v[62:65], v[104:105], off nt
	s_nop 0
	v_addc_co_u32_e32 v103, vcc, -1, v101, vcc
	v_add_co_u32_e32 v116, vcc, 0xfc800000, v98
	global_load_dwordx4 v[58:61], v[102:103], off offset:-3072 nt
	global_load_dwordx4 v[54:57], v[102:103], off offset:-2048 nt
	global_load_dwordx4 v[50:53], v[102:103], off offset:-1024 nt
	global_load_dwordx4 v[46:49], v[100:101], off offset:-4096 nt
	global_load_dwordx4 v[42:45], v[100:101], off offset:-3072 nt
	global_load_dwordx4 v[38:41], v[100:101], off offset:-2048 nt
	global_load_dwordx4 v[34:37], v[100:101], off offset:-1024 nt
	v_addc_co_u32_e32 v117, vcc, -1, v99, vcc
	v_add_co_u32_e32 v124, vcc, 0xfd000000, v98
	global_load_dwordx2 v[122:123], v[116:117], off offset:-512 nt
	s_nop 0
	v_addc_co_u32_e32 v125, vcc, -1, v99, vcc
	global_load_dwordx2 v[120:121], v[124:125], off offset:-512 nt
	v_add_co_u32_e32 v126, vcc, 0xfd800000, v98
	s_cmpk_gt_i32 s30, 0x3fff
	s_nop 0
	v_addc_co_u32_e32 v127, vcc, -1, v99, vcc
	global_load_dwordx2 v[118:119], v[126:127], off offset:-512 nt
	v_add_co_u32_e32 v128, vcc, 0xfe000000, v98
	s_nop 1
	v_addc_co_u32_e32 v129, vcc, -1, v99, vcc
	global_load_dwordx2 v[112:113], v[128:129], off offset:-512 nt
	v_add_co_u32_e32 v130, vcc, 0xfe800000, v98
	s_waitcnt vmcnt(3)
	v_and_b32_e32 v141, 0xffff0000, v123
	v_addc_co_u32_e32 v131, vcc, -1, v99, vcc
	global_load_dwordx2 v[108:109], v[130:131], off offset:-512 nt
	v_add_co_u32_e32 v134, vcc, 0xff000000, v98
	v_lshlrev_b32_e32 v140, 16, v123
	s_nop 0
	v_addc_co_u32_e32 v135, vcc, -1, v99, vcc
	global_load_dwordx2 v[154:155], v[134:135], off offset:-512 nt
	v_add_co_u32_e32 v136, vcc, 0xff800000, v98
	s_waitcnt vmcnt(4)
	v_and_b32_e32 v149, 0xffff0000, v121
	v_addc_co_u32_e32 v137, vcc, -1, v99, vcc
	global_load_dwordx2 v[114:115], v[136:137], off offset:-512 nt
	global_load_dwordx2 v[110:111], v[98:99], off offset:-512 nt
	global_load_dwordx4 v[94:97], v[100:101], off nt
	global_load_dwordx4 v[90:93], v[100:101], off offset:1024 nt
	global_load_dwordx4 v[86:89], v[100:101], off offset:2048 nt
	global_load_dwordx4 v[82:85], v[100:101], off offset:3072 nt
	v_add_co_u32_e32 v106, vcc, s5, v100
	v_lshlrev_b32_e32 v148, 16, v121
	s_nop 0
	v_addc_co_u32_e32 v107, vcc, 0, v101, vcc
	global_load_dwordx4 v[78:81], v[106:107], off nt
	global_load_dwordx4 v[74:77], v[106:107], off offset:1024 nt
	global_load_dwordx4 v[70:73], v[106:107], off offset:2048 nt
	global_load_dwordx4 v[66:69], v[106:107], off offset:3072 nt
	global_load_dwordx2 v[156:157], v[116:117], off nt
	global_load_dwordx2 v[152:153], v[124:125], off nt
	global_load_dwordx2 v[150:151], v[126:127], off nt
	global_load_dwordx2 v[142:143], v[128:129], off nt
	global_load_dwordx2 v[132:133], v[130:131], off nt
	s_nop 0
	global_load_dwordx2 v[124:125], v[134:135], off nt
	global_load_dwordx2 v[116:117], v[136:137], off nt
	global_load_dwordx2 v[146:147], v[98:99], off nt
	v_and_b32_e32 v131, 0xffff0000, v122
	v_lshlrev_b32_e32 v130, 16, v122
	v_mul_f32_e32 v1, v131, v131
	v_mul_f32_e32 v122, v141, v141
	v_and_b32_e32 v137, 0xffff0000, v120
	v_fmac_f32_e32 v1, v130, v130
	v_fmac_f32_e32 v122, v140, v140
	v_lshlrev_b32_e32 v136, 16, v120
	v_mul_f32_e32 v120, v137, v137
	v_add_f32_e32 v1, v1, v122
	v_fmac_f32_e32 v120, v136, v136
	v_add_f32_e32 v1, v1, v120
	v_mul_f32_e32 v120, v149, v149
	s_waitcnt vmcnt(21)
	v_and_b32_e32 v139, 0xffff0000, v118
	v_fmac_f32_e32 v120, v148, v148
	v_lshlrev_b32_e32 v138, 16, v118
	v_mul_f32_e32 v118, v139, v139
	v_add_f32_e32 v1, v120, v1
	v_fmac_f32_e32 v118, v138, v138
	v_and_b32_e32 v145, 0xffff0000, v119
	v_add_f32_e32 v1, v118, v1
	v_lshlrev_b32_e32 v144, 16, v119
	v_mul_f32_e32 v118, v145, v145
	s_waitcnt vmcnt(20)
	v_and_b32_e32 v129, 0xffff0000, v112
	v_fmac_f32_e32 v118, v144, v144
	v_lshlrev_b32_e32 v128, 16, v112
	v_mul_f32_e32 v112, v129, v129
	v_add_f32_e32 v1, v118, v1
	v_fmac_f32_e32 v112, v128, v128
	v_and_b32_e32 v135, 0xffff0000, v113
	v_add_f32_e32 v1, v112, v1
	v_lshlrev_b32_e32 v134, 16, v113
	v_mul_f32_e32 v112, v135, v135
	v_fmac_f32_e32 v112, v134, v134
	v_add_f32_e32 v1, v112, v1
	v_lshl_add_u64 v[98:99], v[98:99], 0, s[8:9]
	s_waitcnt vmcnt(19)
	v_and_b32_e32 v123, 0xffff0000, v108
	v_lshlrev_b32_e32 v122, 16, v108
	v_mul_f32_e32 v108, v123, v123
	v_fmac_f32_e32 v108, v122, v122
	v_and_b32_e32 v127, 0xffff0000, v109
	v_add_f32_e32 v1, v108, v1
	v_lshlrev_b32_e32 v126, 16, v109
	v_mul_f32_e32 v108, v127, v127
	v_fmac_f32_e32 v108, v126, v126
	s_waitcnt vmcnt(18)
	v_and_b32_e32 v119, 0xffff0000, v154
	v_add_f32_e32 v1, v108, v1
	v_lshlrev_b32_e32 v118, 16, v154
	v_mul_f32_e32 v108, v119, v119
	v_fmac_f32_e32 v108, v118, v118
	v_and_b32_e32 v121, 0xffff0000, v155
	v_add_f32_e32 v1, v108, v1
	v_lshlrev_b32_e32 v120, 16, v155
	v_mul_f32_e32 v108, v121, v121
	v_fmac_f32_e32 v108, v120, v120
	s_waitcnt vmcnt(17)
	v_and_b32_e32 v113, 0xffff0000, v114
	v_add_f32_e32 v1, v108, v1
	v_lshlrev_b32_e32 v112, 16, v114
	v_mul_f32_e32 v108, v113, v113
	v_fmac_f32_e32 v108, v112, v112
	v_lshlrev_b32_e32 v114, 16, v115
	v_and_b32_e32 v115, 0xffff0000, v115
	v_add_f32_e32 v1, v108, v1
	v_mul_f32_e32 v108, v115, v115
	v_fmac_f32_e32 v108, v114, v114
	s_waitcnt vmcnt(16)
	v_and_b32_e32 v109, 0xffff0000, v110
	v_add_f32_e32 v1, v108, v1
	v_lshlrev_b32_e32 v108, 16, v110
	v_mul_f32_e32 v110, v109, v109
	v_fmac_f32_e32 v110, v108, v108
	v_add_f32_e32 v1, v110, v1
	v_lshlrev_b32_e32 v110, 16, v111
	v_and_b32_e32 v111, 0xffff0000, v111
	v_mul_f32_e32 v154, v111, v111
	v_fmac_f32_e32 v154, v110, v110
	v_add_f32_e32 v1, v154, v1
	s_waitcnt vmcnt(6)
; __device__ __forceinline__ float bf2f(unsigned h) { return __uint_as_float(h << 16); }
; template <int MODE> ...
;     ...
;             float rstd[RPW];
; #pragma unroll
;             for (int rr = 0; rr < RPW; ++rr) { float s = 0.f;
; #pragma unroll
;                 for (int k = 0; k < 8; ++k)
; #pragma unroll
;                     for (int e = 0; e < 2; ++e) { const float a = bf2f(yy[rr][k][e] & 0xffffu), b = bf2f(yy[rr][k][e] >> 16); s += a * a + b * b; }
;                 rstd[rr] = 1.0f / sqrtf(wave_sum(s) * (1.f / DM) + RMS_EPS); }
	v_and_b32_e32 v161, 0xffff0000, v152
	s_waitcnt vmcnt(5)
	v_and_b32_e32 v163, 0xffff0000, v150
	v_add_f32_dpp v1, v1, v1 quad_perm:[1,0,3,2] row_mask:0xf bank_mask:0xf bound_ctrl:1
	v_lshlrev_b32_e32 v162, 16, v150
	v_mul_f32_e32 v150, v163, v163
	v_add_f32_dpp v1, v1, v1 quad_perm:[2,3,0,1] row_mask:0xf bank_mask:0xf bound_ctrl:1
	v_fmac_f32_e32 v150, v162, v162
	s_waitcnt vmcnt(4)
	v_and_b32_e32 v165, 0xffff0000, v142
	v_add_f32_dpp v1, v1, v1 row_half_mirror row_mask:0xf bank_mask:0xf bound_ctrl:1
	v_lshlrev_b32_e32 v164, 16, v142
	v_mul_f32_e32 v142, v165, v165
	v_add_f32_dpp v1, v1, v1 row_mirror row_mask:0xf bank_mask:0xf bound_ctrl:1
	v_mov_b32_e32 v154, v1
	s_nop 1
	v_permlane16_swap_b32_e32 v1, v154
	v_add_f32_e32 v1, v1, v154
	v_mov_b32_e32 v154, v1
	s_nop 1
	v_permlane32_swap_b32_e32 v1, v154
	v_add_f32_e32 v1, v1, v154
	v_fmamk_f32 v1, v1, 0x3a000000, v218
	v_cmp_gt_f32_e32 vcc, s14, v1
	v_mul_f32_e32 v154, 0x4f800000, v1
	v_fmac_f32_e32 v142, v164, v164
	v_cndmask_b32_e32 v1, v1, v154, vcc
	v_sqrt_f32_e32 v154, v1
	s_waitcnt vmcnt(3)
	v_and_b32_e32 v167, 0xffff0000, v132
	v_lshlrev_b32_e32 v166, 16, v132
	v_mul_f32_e32 v132, v167, v167
	v_add_u32_e32 v155, -1, v154
	v_fma_f32 v158, -v155, v154, v1
	v_cmp_ge_f32_e64 s[40:41], 0, v158
	v_add_u32_e32 v158, 1, v154
	v_fmac_f32_e32 v132, v166, v166
	v_cndmask_b32_e64 v155, v154, v155, s[40:41]
	v_fma_f32 v154, -v158, v154, v1
	v_cmp_lt_f32_e64 s[40:41], 0, v154
	s_waitcnt vmcnt(2)
	v_and_b32_e32 v169, 0xffff0000, v124
	v_lshlrev_b32_e32 v168, 16, v124
	v_cndmask_b32_e64 v154, v155, v158, s[40:41]
	v_mul_f32_e32 v155, 0x37800000, v154
	v_cndmask_b32_e32 v154, v154, v155, vcc
	v_cmp_class_f32_e32 vcc, v1, v215
	v_mul_f32_e32 v124, v169, v169
	v_fmac_f32_e32 v124, v168, v168
	v_cndmask_b32_e32 v1, v154, v1, vcc
	v_div_scale_f32 v154, s[0:1], v1, v1, 1.0
	v_rcp_f32_e32 v155, v154
	s_waitcnt vmcnt(1)
	v_and_b32_e32 v171, 0xffff0000, v116
	v_lshlrev_b32_e32 v170, 16, v116
	v_mul_f32_e32 v116, v171, v171
	v_fma_f32 v158, -v154, v155, 1.0
	v_fmac_f32_e32 v155, v158, v155
	v_div_scale_f32 v158, vcc, 1.0, v1, 1.0
	v_mul_f32_e32 v159, v158, v155
	v_fma_f32 v160, -v154, v159, v158
	v_fmac_f32_e32 v159, v160, v155
	v_fma_f32 v154, -v154, v159, v158
	v_div_fmas_f32 v154, v154, v155, v159
	v_lshlrev_b32_e32 v158, 16, v156
	v_and_b32_e32 v159, 0xffff0000, v156
	v_lshlrev_b32_e32 v156, 16, v157
	v_and_b32_e32 v157, 0xffff0000, v157
	v_div_fixup_f32 v154, v154, v1, 1.0
	v_mul_f32_e32 v1, v159, v159
	v_mul_f32_e32 v155, v157, v157
	v_fmac_f32_e32 v1, v158, v158
	v_fmac_f32_e32 v155, v156, v156
	v_lshlrev_b32_e32 v160, 16, v152
	v_mul_f32_e32 v152, v161, v161
	v_add_f32_e32 v1, v1, v155
	v_fmac_f32_e32 v152, v160, v160
	v_add_f32_e32 v1, v1, v152
	v_lshlrev_b32_e32 v152, 16, v153
	v_and_b32_e32 v153, 0xffff0000, v153
	v_mul_f32_e32 v155, v153, v153
	v_fmac_f32_e32 v155, v152, v152
	v_add_f32_e32 v1, v155, v1
	v_add_f32_e32 v1, v150, v1
	v_lshlrev_b32_e32 v150, 16, v151
	v_and_b32_e32 v151, 0xffff0000, v151
	v_mul_f32_e32 v155, v151, v151
	v_fmac_f32_e32 v155, v150, v150
	v_add_f32_e32 v1, v155, v1
	v_add_f32_e32 v1, v142, v1
	v_lshlrev_b32_e32 v142, 16, v143
	v_and_b32_e32 v143, 0xffff0000, v143
	v_mul_f32_e32 v155, v143, v143
	v_fmac_f32_e32 v155, v142, v142
	v_add_f32_e32 v1, v155, v1
	v_add_f32_e32 v1, v132, v1
	v_lshlrev_b32_e32 v132, 16, v133
	v_and_b32_e32 v133, 0xffff0000, v133
	v_mul_f32_e32 v155, v133, v133
	v_fmac_f32_e32 v155, v132, v132
	v_add_f32_e32 v1, v155, v1
	v_add_f32_e32 v1, v124, v1
	v_lshlrev_b32_e32 v124, 16, v125
	v_and_b32_e32 v125, 0xffff0000, v125
	v_mul_f32_e32 v155, v125, v125
	v_fmac_f32_e32 v155, v124, v124
	v_add_f32_e32 v1, v155, v1
	v_fmac_f32_e32 v116, v170, v170
	v_and_b32_e32 v173, 0xffff0000, v117
	v_add_f32_e32 v1, v116, v1
	v_lshlrev_b32_e32 v172, 16, v117
	v_mul_f32_e32 v116, v173, v173
	v_fmac_f32_e32 v116, v172, v172
	s_waitcnt vmcnt(0)
; __device__ __forceinline__ float bf2f(unsigned h) { return __uint_as_float(h << 16); }
; template <int MODE> ...
;     ...
;                 rstd[rr] = 1.0f / sqrtf(wave_sum(s) * (1.f / DM) + RMS_EPS); }
; #pragma unroll
;             for (int k = 0; k < 8; ++k) { const f32x4 g = *(const f32x4*)(gpost + k * 256 + lane * 4);
; #pragma unroll
;                 for (int rr = 0; rr < RPW; ++rr) { f32x4 yv;
;                     yv[0] = bf2f(yy[rr][k][0] & 0xffffu); yv[1] = bf2f(yy[rr][k][0] >> 16); yv[2] = bf2f(yy[rr][k][1] & 0xffffu); yv[3] = bf2f(yy[rr][k][1] >> 16);
;                     xv[rr][k] += yv * rstd[rr] * g; } }
;         }
;         if (MODE != 0)
; #pragma unroll
;         for (int rr = 0; rr < RPW; ++rr) { float* xo = xres + (size_t)(m + rr) * DM + lane * 4;
; #pragma unroll
;             for (int k = 0; k < 8; ++k) *(f32x4*)(xo + k * 256) = xv[rr][k]; }
	v_and_b32_e32 v117, 0xffff0000, v146
	v_add_f32_e32 v1, v116, v1
	v_lshlrev_b32_e32 v116, 16, v146
	v_mul_f32_e32 v146, v117, v117
	v_fmac_f32_e32 v146, v116, v116
	v_add_f32_e32 v1, v146, v1
	v_lshlrev_b32_e32 v146, 16, v147
	v_and_b32_e32 v147, 0xffff0000, v147
	v_mul_f32_e32 v155, v147, v147
	v_fmac_f32_e32 v155, v146, v146
	v_add_f32_e32 v1, v155, v1
	s_nop 1
	v_add_f32_dpp v1, v1, v1 quad_perm:[1,0,3,2] row_mask:0xf bank_mask:0xf bound_ctrl:1
	s_nop 1
	v_add_f32_dpp v1, v1, v1 quad_perm:[2,3,0,1] row_mask:0xf bank_mask:0xf bound_ctrl:1
	s_nop 1
	v_add_f32_dpp v1, v1, v1 row_half_mirror row_mask:0xf bank_mask:0xf bound_ctrl:1
	s_nop 1
	v_add_f32_dpp v1, v1, v1 row_mirror row_mask:0xf bank_mask:0xf bound_ctrl:1
	v_mov_b32_e32 v155, v1
	s_nop 1
	v_permlane16_swap_b32_e32 v1, v155
	v_add_f32_e32 v1, v1, v155
	v_mov_b32_e32 v155, v1
	s_nop 1
	v_permlane32_swap_b32_e32 v1, v155
	v_add_f32_e32 v1, v1, v155
	v_fmamk_f32 v1, v1, 0x3a000000, v218
	v_cmp_gt_f32_e32 vcc, s14, v1
	v_mul_f32_e32 v155, 0x4f800000, v1
	s_nop 0
	v_cndmask_b32_e32 v1, v1, v155, vcc
	v_sqrt_f32_e32 v155, v1
	s_nop 0
	v_add_u32_e32 v174, -1, v155
	v_fma_f32 v175, -v174, v155, v1
	v_cmp_ge_f32_e64 s[40:41], 0, v175
	v_add_u32_e32 v175, 1, v155
	s_nop 0
	v_cndmask_b32_e64 v174, v155, v174, s[40:41]
	v_fma_f32 v155, -v175, v155, v1
	v_cmp_lt_f32_e64 s[40:41], 0, v155
	s_nop 1
	v_cndmask_b32_e64 v155, v174, v175, s[40:41]
	v_mul_f32_e32 v174, 0x37800000, v155
	v_cndmask_b32_e32 v155, v155, v174, vcc
	v_cmp_class_f32_e32 vcc, v1, v215
	s_nop 1
	v_cndmask_b32_e32 v1, v155, v1, vcc
	v_div_scale_f32 v155, s[0:1], v1, v1, 1.0
	v_rcp_f32_e32 v174, v155
	s_nop 0
	v_fma_f32 v175, -v155, v174, 1.0
	v_fmac_f32_e32 v174, v175, v174
	v_div_scale_f32 v175, vcc, 1.0, v1, 1.0
	v_mul_f32_e32 v176, v175, v174
	v_fma_f32 v177, -v155, v176, v175
	v_fmac_f32_e32 v176, v177, v174
	v_fma_f32 v155, -v155, v176, v175
	v_div_fmas_f32 v155, v155, v174, v176
	v_div_fixup_f32 v174, v155, v1, 1.0
	v_pk_mul_f32 v[130:131], v[154:155], v[130:131] op_sel_hi:[0,1]
	v_pk_fma_f32 v[62:63], v[2:3], v[130:131], v[62:63]
	v_pk_mul_f32 v[130:131], v[174:175], v[158:159] op_sel_hi:[0,1]
	v_pk_fma_f32 v[94:95], v[2:3], v[130:131], v[94:95]
	v_pk_mul_f32 v[130:131], v[154:155], v[136:137] op_sel_hi:[0,1]
	v_pk_fma_f32 v[58:59], v[6:7], v[130:131], v[58:59]
	v_pk_mul_f32 v[130:131], v[174:175], v[160:161] op_sel_hi:[0,1]
	v_pk_mul_f32 v[136:137], v[154:155], v[148:149] op_sel_hi:[0,1]
	v_pk_fma_f32 v[90:91], v[6:7], v[130:131], v[90:91]
	v_pk_mul_f32 v[130:131], v[154:155], v[138:139] op_sel_hi:[0,1]
	v_pk_fma_f32 v[60:61], v[8:9], v[136:137], v[60:61]
	v_pk_mul_f32 v[136:137], v[174:175], v[152:153] op_sel_hi:[0,1]
	v_pk_fma_f32 v[54:55], v[10:11], v[130:131], v[54:55]
	v_pk_mul_f32 v[130:131], v[174:175], v[162:163] op_sel_hi:[0,1]
	v_pk_mul_f32 v[140:141], v[154:155], v[140:141] op_sel_hi:[0,1]
	v_pk_fma_f32 v[92:93], v[8:9], v[136:137], v[92:93]
	v_pk_mul_f32 v[136:137], v[154:155], v[144:145] op_sel_hi:[0,1]
	v_pk_fma_f32 v[86:87], v[10:11], v[130:131], v[86:87]
	v_pk_mul_f32 v[128:129], v[154:155], v[128:129] op_sel_hi:[0,1]
	v_pk_mul_f32 v[130:131], v[154:155], v[134:135] op_sel_hi:[0,1]
	v_pk_mul_f32 v[122:123], v[154:155], v[122:123] op_sel_hi:[0,1]
	v_pk_mul_f32 v[126:127], v[154:155], v[126:127] op_sel_hi:[0,1]
	v_pk_mul_f32 v[118:119], v[154:155], v[118:119] op_sel_hi:[0,1]
	v_pk_mul_f32 v[120:121], v[154:155], v[120:121] op_sel_hi:[0,1]
	v_pk_mul_f32 v[112:113], v[154:155], v[112:113] op_sel_hi:[0,1]
	v_pk_mul_f32 v[114:115], v[154:155], v[114:115] op_sel_hi:[0,1]
	v_pk_mul_f32 v[108:109], v[154:155], v[108:109] op_sel_hi:[0,1]
	v_pk_mul_f32 v[110:111], v[154:155], v[110:111] op_sel_hi:[0,1]
	v_pk_fma_f32 v[64:65], v[4:5], v[140:141], v[64:65]
	v_pk_mul_f32 v[140:141], v[174:175], v[156:157] op_sel_hi:[0,1]
	v_pk_fma_f32 v[56:57], v[12:13], v[136:137], v[56:57]
	v_pk_mul_f32 v[136:137], v[174:175], v[150:151] op_sel_hi:[0,1]
	v_pk_fma_f32 v[52:53], v[16:17], v[130:131], v[52:53]
	v_pk_fma_f32 v[50:51], v[14:15], v[128:129], v[50:51]
	v_pk_mul_f32 v[128:129], v[174:175], v[164:165] op_sel_hi:[0,1]
	v_pk_mul_f32 v[130:131], v[174:175], v[142:143] op_sel_hi:[0,1]
	v_pk_fma_f32 v[48:49], v[20:21], v[126:127], v[48:49]
	v_pk_fma_f32 v[46:47], v[18:19], v[122:123], v[46:47]
	v_pk_mul_f32 v[122:123], v[174:175], v[166:167] op_sel_hi:[0,1]
	v_pk_mul_f32 v[126:127], v[174:175], v[132:133] op_sel_hi:[0,1]
	v_pk_fma_f32 v[44:45], v[24:25], v[120:121], v[44:45]
	v_pk_fma_f32 v[42:43], v[22:23], v[118:119], v[42:43]
	v_pk_mul_f32 v[118:119], v[174:175], v[168:169] op_sel_hi:[0,1]
	v_pk_mul_f32 v[120:121], v[174:175], v[124:125] op_sel_hi:[0,1]
	v_pk_fma_f32 v[40:41], v[28:29], v[114:115], v[40:41]
	v_pk_fma_f32 v[38:39], v[26:27], v[112:113], v[38:39]
	v_pk_mul_f32 v[112:113], v[174:175], v[170:171] op_sel_hi:[0,1]
	v_pk_mul_f32 v[114:115], v[174:175], v[172:173] op_sel_hi:[0,1]
	v_pk_fma_f32 v[36:37], v[32:33], v[110:111], v[36:37]
	v_pk_fma_f32 v[34:35], v[30:31], v[108:109], v[34:35]
	v_pk_mul_f32 v[108:109], v[174:175], v[116:117] op_sel_hi:[0,1]
	v_pk_mul_f32 v[110:111], v[174:175], v[146:147] op_sel_hi:[0,1]
	v_pk_fma_f32 v[96:97], v[4:5], v[140:141], v[96:97]
	v_pk_fma_f32 v[88:89], v[12:13], v[136:137], v[88:89]
	v_pk_fma_f32 v[84:85], v[16:17], v[130:131], v[84:85]
	v_pk_fma_f32 v[82:83], v[14:15], v[128:129], v[82:83]
	v_pk_fma_f32 v[80:81], v[20:21], v[126:127], v[80:81]
	v_pk_fma_f32 v[78:79], v[18:19], v[122:123], v[78:79]
	v_pk_fma_f32 v[76:77], v[24:25], v[120:121], v[76:77]
	v_pk_fma_f32 v[74:75], v[22:23], v[118:119], v[74:75]
	v_pk_fma_f32 v[72:73], v[28:29], v[114:115], v[72:73]
	v_pk_fma_f32 v[70:71], v[26:27], v[112:113], v[70:71]
	v_pk_fma_f32 v[68:69], v[32:33], v[110:111], v[68:69]
	v_pk_fma_f32 v[66:67], v[30:31], v[108:109], v[66:67]
	global_store_dwordx4 v[104:105], v[62:65], off sc0 sc1
	global_store_dwordx4 v[102:103], v[58:61], off offset:-3072 sc0 sc1
	global_store_dwordx4 v[102:103], v[54:57], off offset:-2048 sc0 sc1
	global_store_dwordx4 v[102:103], v[50:53], off offset:-1024 sc0 sc1
	global_store_dwordx4 v[100:101], v[46:49], off offset:-4096 sc0 sc1
	global_store_dwordx4 v[100:101], v[42:45], off offset:-3072 sc0 sc1
	global_store_dwordx4 v[100:101], v[38:41], off offset:-2048 sc0 sc1
	global_store_dwordx4 v[100:101], v[34:37], off offset:-1024 sc0 sc1
	global_store_dwordx4 v[100:101], v[94:97], off sc0 sc1
	global_store_dwordx4 v[100:101], v[90:93], off offset:1024 sc0 sc1
	global_store_dwordx4 v[100:101], v[86:89], off offset:2048 sc0 sc1
	global_store_dwordx4 v[100:101], v[82:85], off offset:3072 sc0 sc1
	global_store_dwordx4 v[106:107], v[78:81], off sc0 sc1
	global_store_dwordx4 v[106:107], v[74:77], off offset:1024 sc0 sc1
	global_store_dwordx4 v[106:107], v[70:73], off offset:2048 sc0 sc1
	global_store_dwordx4 v[106:107], v[66:69], off offset:3072 sc0 sc1
	v_lshl_add_u64 v[100:101], v[100:101], 0, s[12:13]
	s_cbranch_scc0 .LBB0_230
